# also: step-0 conv loops 4 elements per trip with batched loads; weight-convert loops issue their 8 tile loads before one wait
# speedup vs baseline: 1.0512x; 1.0139x over previous
; __device__ void convert_wt(unsigned char* shm, const float* W, int K, int ldw, int c0, int ncols, bf16_t* Bt, int blk, int off) {
;     ...
;   for (int t = blockIdx.x; t < ntile; t += gridDim.x) {
;     const int kt = t % tk, nt_ = t / tk;
;     __syncthreads();
; #pragma unroll
;     for (int i = 0; i < 8; ++i) { const int e = tid + i * 512, r = e >> 6, c = e & 63; tile[r * 65 + c] = W[(size_t)(kt * 64 + r) * ldw + c0 + nt_ * 64 + c]; }
.LBB0_95:
	s_ashr_i32 s7, s5, 31
	s_lshr_b32 s7, s7, 27
	s_add_i32 s7, s5, s7
	s_ashr_i32 s11, s7, 5
	s_lshl_b32 s14, s11, 6
	s_lshl_b32 s11, s11, 11
	s_ashr_i32 s15, s14, 31
	s_sub_i32 s11, s17, s11
	v_lshl_add_u64 v[28:29], s[14:15], 2, v[0:1]
	v_add_u32_e32 v3, s11, v5
	v_mad_i64_i32 v[30:31], s[20:21], v3, s64, v[28:29]
	s_barrier
	global_load_dword v230, v[30:31], off
	s_andn2_b32 s7, s7, 31
	v_add_u32_e32 v5, s57, v5


; __device__ void convert_wt(unsigned char* shm, const float* W, int K, int ldw, int c0, int ncols, bf16_t* Bt, int blk, int off) {
;     ...
;     for (int i = 0; i < 8; ++i) { const int e = tid + i * 512, r = e >> 6, c = e & 63; tile[r * 65 + c] = W[(size_t)(kt * 64 + r) * ldw + c0 + nt_ * 64 + c]; }
	v_add_u32_e32 v3, s11, v6
	v_mad_i64_i32 v[30:31], s[20:21], v3, s64, v[28:29]
	global_load_dword v231, v[30:31], off
	v_add_u32_e32 v6, s57, v6


; __device__ void convert_wt(unsigned char* shm, const float* W, int K, int ldw, int c0, int ncols, bf16_t* Bt, int blk, int off) {
;     ...
;     for (int i = 0; i < 8; ++i) { const int e = tid + i * 512, r = e >> 6, c = e & 63; tile[r * 65 + c] = W[(size_t)(kt * 64 + r) * ldw + c0 + nt_ * 64 + c]; }
	v_add_u32_e32 v3, s11, v7
	v_mad_i64_i32 v[30:31], s[20:21], v3, s64, v[28:29]
	global_load_dword v232, v[30:31], off
	v_add_u32_e32 v7, s57, v7


; __device__ void convert_wt(unsigned char* shm, const float* W, int K, int ldw, int c0, int ncols, bf16_t* Bt, int blk, int off) {
;     ...
;     for (int i = 0; i < 8; ++i) { const int e = tid + i * 512, r = e >> 6, c = e & 63; tile[r * 65 + c] = W[(size_t)(kt * 64 + r) * ldw + c0 + nt_ * 64 + c]; }
	v_add_u32_e32 v3, s11, v8
	v_mad_i64_i32 v[30:31], s[20:21], v3, s64, v[28:29]
	global_load_dword v233, v[30:31], off
	v_add_u32_e32 v8, s57, v8


; __device__ void convert_wt(unsigned char* shm, const float* W, int K, int ldw, int c0, int ncols, bf16_t* Bt, int blk, int off) {
;     ...
;     for (int i = 0; i < 8; ++i) { const int e = tid + i * 512, r = e >> 6, c = e & 63; tile[r * 65 + c] = W[(size_t)(kt * 64 + r) * ldw + c0 + nt_ * 64 + c]; }
	v_add_u32_e32 v3, s11, v9
	v_mad_i64_i32 v[30:31], s[20:21], v3, s64, v[28:29]
	global_load_dword v234, v[30:31], off
	v_add_u32_e32 v9, s57, v9


; __device__ void convert_wt(unsigned char* shm, const float* W, int K, int ldw, int c0, int ncols, bf16_t* Bt, int blk, int off) {
;     ...
;     for (int i = 0; i < 8; ++i) { const int e = tid + i * 512, r = e >> 6, c = e & 63; tile[r * 65 + c] = W[(size_t)(kt * 64 + r) * ldw + c0 + nt_ * 64 + c]; }
	v_add_u32_e32 v3, s11, v10
	v_mad_i64_i32 v[30:31], s[20:21], v3, s64, v[28:29]
	global_load_dword v235, v[30:31], off
	v_add_u32_e32 v10, s57, v10


; __device__ void convert_wt(unsigned char* shm, const float* W, int K, int ldw, int c0, int ncols, bf16_t* Bt, int blk, int off) {
;     ...
;     for (int i = 0; i < 8; ++i) { const int e = tid + i * 512, r = e >> 6, c = e & 63; tile[r * 65 + c] = W[(size_t)(kt * 64 + r) * ldw + c0 + nt_ * 64 + c]; }
	v_add_u32_e32 v3, s11, v11
	v_mad_i64_i32 v[30:31], s[20:21], v3, s64, v[28:29]
	global_load_dword v236, v[30:31], off
	v_add_u32_e32 v11, s57, v11


; __device__ void convert_wt(unsigned char* shm, const float* W, int K, int ldw, int c0, int ncols, bf16_t* Bt, int blk, int off) {
;     ...
;     for (int i = 0; i < 8; ++i) { const int e = tid + i * 512, r = e >> 6, c = e & 63; tile[r * 65 + c] = W[(size_t)(kt * 64 + r) * ldw + c0 + nt_ * 64 + c]; }
	v_add_u32_e32 v3, s11, v12
	v_mad_i64_i32 v[28:29], s[20:21], v3, s64, v[28:29]
	global_load_dword v237, v[28:29], off
	s_waitcnt vmcnt(0)
	ds_write_b32 v20, v230
	ds_write_b32 v21, v231
	ds_write_b32 v22, v232
	ds_write_b32 v23, v233
	ds_write_b32 v24, v234
	ds_write_b32 v25, v235
	ds_write_b32 v26, v236
	ds_write_b32 v27, v237
	v_add_u32_e32 v12, s57, v12


; __device__ __forceinline__ unsigned cvt_pk_bf16(float lo, float hi) { unsigned r; asm volatile("v_cvt_pk_bf16_f32 %0, %1, %2" : "=v"(r) : "v"(lo), "v"(hi)); return r; }
; __device__ void convert_wt(unsigned char* shm, const float* W, int K, int ldw, int c0, int ncols, bf16_t* Bt, int blk, int off) {
;     ...
;     __syncthreads();
; #pragma unroll
;     for (int i = 0; i < 4; ++i) { const int e = tid + i * 512, n = e >> 5, kp = (e & 31) * 2; const int c = nt_ * 64 + n;
;       const unsigned w = cvt_pk_bf16(tile[kp * 65 + n], tile[(kp + 1) * 65 + n]);
;       const int nr = (c >> 7) * blk + off + (c & 127);
;       *(unsigned*)(Bt + ((size_t)((nr >> 8) * tk + kt) * 256 + (nr & 255)) * 64 + kp) = w; }
	s_waitcnt lgkmcnt(0)
	s_barrier
	v_add_u32_e32 v3, s14, v4
	ds_read2_b32 v[28:29], v13 offset1:65
	s_waitcnt lgkmcnt(0)
	v_cvt_pk_bf16_f32 v30, v28, v29
	v_ashrrev_i32_e32 v28, 2, v3
	v_and_b32_e32 v28, 0xffffffe0, v28
	v_subrev_u32_e32 v28, s7, v28
	v_add_u32_e32 v28, s5, v28
	v_ashrrev_i32_e32 v29, 31, v28
	v_lshlrev_b64 v[28:29], 15, v[28:29]
	v_lshlrev_b32_e32 v3, 7, v3
	v_lshl_add_u64 v[28:29], s[24:25], 0, v[28:29]
	v_and_b32_e32 v32, 0x3f80, v3
	v_lshl_add_u64 v[28:29], v[28:29], 0, v[32:33]
	v_mov_b32_e32 v3, v33
	v_lshl_add_u64 v[28:29], v[28:29], 0, v[2:3]
	global_store_dword v[28:29], v30, off
	v_add_u32_e32 v30, s14, v14
	ds_read2_b32 v[28:29], v15 offset1:65
	s_waitcnt lgkmcnt(0)
	v_cvt_pk_bf16_f32 v31, v28, v29
	v_ashrrev_i32_e32 v28, 2, v30
	v_and_b32_e32 v28, 0xffffffe0, v28
	v_subrev_u32_e32 v28, s7, v28
	v_add_u32_e32 v28, s5, v28
	v_ashrrev_i32_e32 v29, 31, v28
	v_lshlrev_b64 v[28:29], 15, v[28:29]
	v_lshlrev_b32_e32 v30, 7, v30
	v_lshl_add_u64 v[28:29], s[24:25], 0, v[28:29]
	v_and_b32_e32 v32, 0x3f80, v30
	v_lshl_add_u64 v[28:29], v[28:29], 0, v[32:33]
	v_lshl_add_u64 v[28:29], v[28:29], 0, v[2:3]
	global_store_dword v[28:29], v31, off
	v_add_u32_e32 v30, s14, v16
	ds_read2_b32 v[28:29], v17 offset1:65
	s_waitcnt lgkmcnt(0)
	v_cvt_pk_bf16_f32 v31, v28, v29
	v_ashrrev_i32_e32 v28, 2, v30
	v_and_b32_e32 v28, 0xffffffe0, v28
	v_subrev_u32_e32 v28, s7, v28
	v_add_u32_e32 v28, s5, v28
	v_ashrrev_i32_e32 v29, 31, v28
	v_lshlrev_b64 v[28:29], 15, v[28:29]
	v_lshlrev_b32_e32 v30, 7, v30
	v_lshl_add_u64 v[28:29], s[24:25], 0, v[28:29]
	v_and_b32_e32 v32, 0x3f80, v30
	v_lshl_add_u64 v[28:29], v[28:29], 0, v[32:33]
	v_lshl_add_u64 v[28:29], v[28:29], 0, v[2:3]
	global_store_dword v[28:29], v31, off
	v_add_u32_e32 v30, s14, v18
	ds_read2_b32 v[28:29], v19 offset1:65
	s_waitcnt lgkmcnt(0)
	v_cvt_pk_bf16_f32 v31, v28, v29
	v_ashrrev_i32_e32 v28, 2, v30
	v_and_b32_e32 v28, 0xffffffe0, v28
	v_subrev_u32_e32 v28, s7, v28
	v_add_u32_e32 v28, s5, v28
	v_ashrrev_i32_e32 v29, 31, v28
	v_lshlrev_b64 v[28:29], 15, v[28:29]
	v_lshlrev_b32_e32 v30, 7, v30
	v_lshl_add_u64 v[28:29], s[24:25], 0, v[28:29]
	v_and_b32_e32 v32, 0x3f80, v30
	v_lshl_add_u64 v[28:29], v[28:29], 0, v[32:33]
	s_add_i32 s5, s5, s22
	v_lshl_add_u64 v[28:29], v[28:29], 0, v[2:3]
	s_cmpk_lt_i32 s5, 0xb00
	global_store_dword v[28:29], v31, off
	s_cbranch_scc1 .LBB0_95

; __device__ void convert_wt(unsigned char* shm, const float* W, int K, int ldw, int c0, int ncols, bf16_t* Bt, int blk, int off) {
;     ...
;   for (int t = blockIdx.x; t < ntile; t += gridDim.x) {
;     const int kt = t % tk, nt_ = t / tk;
;     __syncthreads();
; #pragma unroll
;     for (int i = 0; i < 8; ++i) { const int e = tid + i * 512, r = e >> 6, c = e & 63; tile[r * 65 + c] = W[(size_t)(kt * 64 + r) * ldw + c0 + nt_ * 64 + c]; }
.LBB0_101:
	s_mul_hi_i32 s7, s5, 0x2e8ba2e9
	s_lshr_b32 s11, s7, 31
	s_ashr_i32 s7, s7, 4
	s_add_i32 s11, s7, s11
	s_mul_i32 s7, s11, 0x58
	s_lshl_b32 s14, s11, 6
	s_mulk_i32 s11, 0xea00
	s_add_i32 s11, s11, s17
	v_add_u32_e32 v30, s11, v7
	s_ashr_i32 s15, s14, 31
	v_ashrrev_i32_e32 v31, 31, v30
	v_lshl_add_u64 v[4:5], s[14:15], 2, v[0:1]
	v_lshlrev_b64 v[30:31], 13, v[30:31]
	v_lshl_add_u64 v[30:31], v[4:5], 0, v[30:31]
	s_barrier
	global_load_dword v230, v[30:31], off
	v_add_u32_e32 v30, s11, v8
	v_ashrrev_i32_e32 v31, 31, v30
	v_lshlrev_b64 v[30:31], 13, v[30:31]
	v_lshl_add_u64 v[30:31], v[4:5], 0, v[30:31]
	v_add_u32_e32 v8, s57, v8
	v_add_u32_e32 v7, s57, v7


; __device__ void convert_wt(unsigned char* shm, const float* W, int K, int ldw, int c0, int ncols, bf16_t* Bt, int blk, int off) {
;     ...
;     for (int i = 0; i < 8; ++i) { const int e = tid + i * 512, r = e >> 6, c = e & 63; tile[r * 65 + c] = W[(size_t)(kt * 64 + r) * ldw + c0 + nt_ * 64 + c]; }
	global_load_dword v231, v[30:31], off
	v_add_u32_e32 v30, s11, v9
	v_ashrrev_i32_e32 v31, 31, v30
	v_lshlrev_b64 v[30:31], 13, v[30:31]
	v_lshl_add_u64 v[30:31], v[4:5], 0, v[30:31]
	v_add_u32_e32 v9, s57, v9


; __device__ void convert_wt(unsigned char* shm, const float* W, int K, int ldw, int c0, int ncols, bf16_t* Bt, int blk, int off) {
;     ...
;     for (int i = 0; i < 8; ++i) { const int e = tid + i * 512, r = e >> 6, c = e & 63; tile[r * 65 + c] = W[(size_t)(kt * 64 + r) * ldw + c0 + nt_ * 64 + c]; }
	global_load_dword v232, v[30:31], off
	v_add_u32_e32 v30, s11, v10
	v_ashrrev_i32_e32 v31, 31, v30
	v_lshlrev_b64 v[30:31], 13, v[30:31]
	v_lshl_add_u64 v[30:31], v[4:5], 0, v[30:31]
	v_add_u32_e32 v10, s57, v10


; __device__ void convert_wt(unsigned char* shm, const float* W, int K, int ldw, int c0, int ncols, bf16_t* Bt, int blk, int off) {
;     ...
;     for (int i = 0; i < 8; ++i) { const int e = tid + i * 512, r = e >> 6, c = e & 63; tile[r * 65 + c] = W[(size_t)(kt * 64 + r) * ldw + c0 + nt_ * 64 + c]; }
	global_load_dword v233, v[30:31], off
	v_add_u32_e32 v30, s11, v11
	v_ashrrev_i32_e32 v31, 31, v30
	v_lshlrev_b64 v[30:31], 13, v[30:31]
	v_lshl_add_u64 v[30:31], v[4:5], 0, v[30:31]
	v_add_u32_e32 v11, s57, v11


; __device__ void convert_wt(unsigned char* shm, const float* W, int K, int ldw, int c0, int ncols, bf16_t* Bt, int blk, int off) {
;     ...
;     for (int i = 0; i < 8; ++i) { const int e = tid + i * 512, r = e >> 6, c = e & 63; tile[r * 65 + c] = W[(size_t)(kt * 64 + r) * ldw + c0 + nt_ * 64 + c]; }
	global_load_dword v234, v[30:31], off
	v_add_u32_e32 v30, s11, v12
	v_ashrrev_i32_e32 v31, 31, v30
	v_lshlrev_b64 v[30:31], 13, v[30:31]
	v_lshl_add_u64 v[30:31], v[4:5], 0, v[30:31]
	v_add_u32_e32 v12, s57, v12


; __device__ void convert_wt(unsigned char* shm, const float* W, int K, int ldw, int c0, int ncols, bf16_t* Bt, int blk, int off) {
;     ...
;     for (int i = 0; i < 8; ++i) { const int e = tid + i * 512, r = e >> 6, c = e & 63; tile[r * 65 + c] = W[(size_t)(kt * 64 + r) * ldw + c0 + nt_ * 64 + c]; }
	global_load_dword v235, v[30:31], off
	v_add_u32_e32 v30, s11, v13
	v_ashrrev_i32_e32 v31, 31, v30
	v_lshlrev_b64 v[30:31], 13, v[30:31]
	v_lshl_add_u64 v[30:31], v[4:5], 0, v[30:31]
	v_add_u32_e32 v13, s57, v13


; __device__ void convert_wt(unsigned char* shm, const float* W, int K, int ldw, int c0, int ncols, bf16_t* Bt, int blk, int off) {
;     ...
;     for (int i = 0; i < 8; ++i) { const int e = tid + i * 512, r = e >> 6, c = e & 63; tile[r * 65 + c] = W[(size_t)(kt * 64 + r) * ldw + c0 + nt_ * 64 + c]; }
	global_load_dword v236, v[30:31], off
	v_add_u32_e32 v30, s11, v14
	v_ashrrev_i32_e32 v31, 31, v30
	v_lshlrev_b64 v[30:31], 13, v[30:31]
	v_lshl_add_u64 v[4:5], v[4:5], 0, v[30:31]
	v_add_u32_e32 v14, s57, v14


; __device__ void convert_wt(unsigned char* shm, const float* W, int K, int ldw, int c0, int ncols, bf16_t* Bt, int blk, int off) {
;     ...
;     for (int i = 0; i < 8; ++i) { const int e = tid + i * 512, r = e >> 6, c = e & 63; tile[r * 65 + c] = W[(size_t)(kt * 64 + r) * ldw + c0 + nt_ * 64 + c]; }
	global_load_dword v237, v[4:5], off
	s_waitcnt vmcnt(0)
	ds_write_b32 v22, v230
	ds_write_b32 v23, v231
	ds_write_b32 v24, v232
	ds_write_b32 v25, v233
	ds_write_b32 v26, v234
	ds_write_b32 v27, v235
	ds_write_b32 v28, v236
	ds_write_b32 v29, v237


; __device__ __forceinline__ unsigned cvt_pk_bf16(float lo, float hi) { unsigned r; asm volatile("v_cvt_pk_bf16_f32 %0, %1, %2" : "=v"(r) : "v"(lo), "v"(hi)); return r; }
; __device__ void convert_wt(unsigned char* shm, const float* W, int K, int ldw, int c0, int ncols, bf16_t* Bt, int blk, int off) {
;     ...
;     __syncthreads();
; #pragma unroll
;     for (int i = 0; i < 4; ++i) { const int e = tid + i * 512, n = e >> 5, kp = (e & 31) * 2; const int c = nt_ * 64 + n;
;       const unsigned w = cvt_pk_bf16(tile[kp * 65 + n], tile[(kp + 1) * 65 + n]);
;       const int nr = (c >> 7) * blk + off + (c & 127);
;       *(unsigned*)(Bt + ((size_t)((nr >> 8) * tk + kt) * 256 + (nr & 255)) * 64 + kp) = w; }
	s_waitcnt lgkmcnt(0)
	s_barrier
	v_add_u32_e32 v3, s14, v6
	ds_read2_b32 v[4:5], v15 offset1:65
	s_waitcnt lgkmcnt(0)
	v_cvt_pk_bf16_f32 v30, v4, v5
	v_lshrrev_b32_e32 v4, 8, v3
	v_mul_i32_i24_e32 v4, 0x58, v4
	v_subrev_u32_e32 v4, s7, v4
	v_add_u32_e32 v4, s5, v4
	v_ashrrev_i32_e32 v5, 31, v4
	v_lshlrev_b64 v[4:5], 15, v[4:5]
	v_lshlrev_b32_e32 v3, 7, v3
	v_lshl_add_u64 v[4:5], s[22:23], 0, v[4:5]
	v_and_b32_e32 v32, 0x7f80, v3
	v_lshl_add_u64 v[4:5], v[4:5], 0, v[32:33]
	v_mov_b32_e32 v3, v33
	v_lshl_add_u64 v[4:5], v[4:5], 0, v[2:3]
	global_store_dword v[4:5], v30, off
	v_add_u32_e32 v30, s14, v16
	ds_read2_b32 v[4:5], v17 offset1:65
	s_waitcnt lgkmcnt(0)
	v_cvt_pk_bf16_f32 v31, v4, v5
	v_lshrrev_b32_e32 v4, 8, v30
	v_mul_i32_i24_e32 v4, 0x58, v4
	v_subrev_u32_e32 v4, s7, v4
	v_add_u32_e32 v4, s5, v4
	v_ashrrev_i32_e32 v5, 31, v4
	v_lshlrev_b64 v[4:5], 15, v[4:5]
	v_lshlrev_b32_e32 v30, 7, v30
	v_lshl_add_u64 v[4:5], s[22:23], 0, v[4:5]
	v_and_b32_e32 v32, 0x7f80, v30
	v_lshl_add_u64 v[4:5], v[4:5], 0, v[32:33]
	v_lshl_add_u64 v[4:5], v[4:5], 0, v[2:3]
	global_store_dword v[4:5], v31, off
	v_add_u32_e32 v30, s14, v18
	ds_read2_b32 v[4:5], v19 offset1:65
	s_waitcnt lgkmcnt(0)
	v_cvt_pk_bf16_f32 v31, v4, v5
	v_lshrrev_b32_e32 v4, 8, v30
	v_mul_i32_i24_e32 v4, 0x58, v4
	v_subrev_u32_e32 v4, s7, v4
	v_add_u32_e32 v4, s5, v4
	v_ashrrev_i32_e32 v5, 31, v4
	v_lshlrev_b64 v[4:5], 15, v[4:5]
	v_lshlrev_b32_e32 v30, 7, v30
	v_lshl_add_u64 v[4:5], s[22:23], 0, v[4:5]
	v_and_b32_e32 v32, 0x7f80, v30
	v_lshl_add_u64 v[4:5], v[4:5], 0, v[32:33]
	v_lshl_add_u64 v[4:5], v[4:5], 0, v[2:3]
	global_store_dword v[4:5], v31, off
	v_add_u32_e32 v30, s14, v20
	ds_read2_b32 v[4:5], v21 offset1:65
	s_waitcnt lgkmcnt(0)
	v_cvt_pk_bf16_f32 v31, v4, v5
	v_lshrrev_b32_e32 v4, 8, v30
	v_mul_i32_i24_e32 v4, 0x58, v4
	v_subrev_u32_e32 v4, s7, v4
	v_add_u32_e32 v4, s5, v4
	v_ashrrev_i32_e32 v5, 31, v4
	v_lshlrev_b64 v[4:5], 15, v[4:5]
	v_lshlrev_b32_e32 v30, 7, v30
	v_lshl_add_u64 v[4:5], s[22:23], 0, v[4:5]
	v_and_b32_e32 v32, 0x7f80, v30
	v_lshl_add_u64 v[4:5], v[4:5], 0, v[32:33]
	s_add_i32 s5, s5, s20
	v_lshl_add_u64 v[4:5], v[4:5], 0, v[2:3]
	s_cmpk_lt_i32 s5, 0xb00
	global_store_dword v[4:5], v31, off
	s_cbranch_scc1 .LBB0_101

; __device__ __forceinline__ unsigned cvt_pk_bf16(float lo, float hi) { unsigned r; asm volatile("v_cvt_pk_bf16_f32 %0, %1, %2" : "=v"(r) : "v"(lo), "v"(hi)); return r; }
; __device__ __forceinline__ float bf2f(bf16_t b) { return __uint_as_float(((unsigned)b) << 16); }
; __device__ __forceinline__ float sconv(const bf16_t* row, int t, int L, float w0, float w1, float w2, float b) {
;   const int tm = t > 0 ? t - 1 : 0, tp = t + 1 < L ? t + 1 : L - 1;
;   const float vm = bf2f(row[tm]), p0 = bf2f(row[t]), vp = bf2f(row[tp]);
;   const float pm = t > 0 ? vm : 0.f, pp = t + 1 < L ? vp : 0.f;
;   return pm * w0 + p0 * w1 + pp * w2 + b;
; template <int LOGN, bool DUAL>
; __device__ void hyena_unit(const Params& p, unsigned char* shm, int ca, int cb, int ka, int kb) {
;     ...
;     const float w0a = cw[ca], w1a = cw[3072 + ca], w2a = cw[6144 + ca], bba = cb_[ca];
;     const float w0b = cw[cb], w1b = cw[3072 + cb], w2b = cw[6144 + cb], bbb = cb_[cb];
;     const bf16_t* r0 = hyT + (size_t)ca * L; const bf16_t* r1 = r0 + seqstride;
; #pragma unroll 4
;     for (int i = tid; i < LX; i += 512) {
;       const int ch = i >> LOGN, t = i & (L - 1);
;       const float w0 = ch ? w0b : w0a, w1 = ch ? w1b : w1a, w2 = ch ? w2b : w2a, bb = ch ? bbb : bba;
;       Wd[i] = cvt_pk_bf16(sconv(r0 + (size_t)ch * rowdiff, t, L, w0, w1, w2, bb), sconv(r1 + (size_t)ch * rowdiff, t, L, w0, w1, w2, bb));
;     }
.LBB0_518:
	v_and_b32_e32 v170, 0x3fff, v0
	v_max_u32_e32 v174, 1, v170
	v_min_u32_e32 v178, 0x3ffe, v170
	v_lshlrev_b32_e32 v182, 1, v170
	v_lshlrev_b32_e32 v174, 1, v174
	v_lshlrev_b32_e32 v178, 1, v178
	v_add_u32_e32 v171, 0x200, v0
	v_and_b32_e32 v171, 0x3fff, v171
	v_max_u32_e32 v175, 1, v171
	v_min_u32_e32 v179, 0x3ffe, v171
	v_lshlrev_b32_e32 v183, 1, v171
	v_lshlrev_b32_e32 v175, 1, v175
	v_lshlrev_b32_e32 v179, 1, v179
	v_add_u32_e32 v172, 0x400, v0
	v_and_b32_e32 v172, 0x3fff, v172
	v_max_u32_e32 v176, 1, v172
	v_min_u32_e32 v180, 0x3ffe, v172
	v_lshlrev_b32_e32 v184, 1, v172
	v_lshlrev_b32_e32 v176, 1, v176
	v_lshlrev_b32_e32 v180, 1, v180
	v_add_u32_e32 v173, 0x600, v0
	v_and_b32_e32 v173, 0x3fff, v173
	v_max_u32_e32 v177, 1, v173
	v_min_u32_e32 v181, 0x3ffe, v173
	v_lshlrev_b32_e32 v185, 1, v173
	v_lshlrev_b32_e32 v177, 1, v177
	v_lshlrev_b32_e32 v181, 1, v181
	global_load_ushort v207, v174, s[48:49] offset:-2
	global_load_ushort v208, v182, s[48:49]
	global_load_ushort v209, v178, s[48:49] offset:2
	global_load_ushort v210, v182, s[50:51]
	global_load_ushort v211, v174, s[50:51] offset:-2
	global_load_ushort v212, v178, s[50:51] offset:2
	global_load_ushort v213, v175, s[48:49] offset:-2
	global_load_ushort v214, v183, s[48:49]
	global_load_ushort v215, v179, s[48:49] offset:2
	global_load_ushort v216, v183, s[50:51]
	global_load_ushort v217, v175, s[50:51] offset:-2
	global_load_ushort v218, v179, s[50:51] offset:2
	global_load_ushort v219, v176, s[48:49] offset:-2
	global_load_ushort v220, v184, s[48:49]
	global_load_ushort v221, v180, s[48:49] offset:2
	global_load_ushort v222, v184, s[50:51]
	global_load_ushort v223, v176, s[50:51] offset:-2
	global_load_ushort v224, v180, s[50:51] offset:2
	global_load_ushort v225, v177, s[48:49] offset:-2
	global_load_ushort v226, v185, s[48:49]
	global_load_ushort v227, v181, s[48:49] offset:2
	global_load_ushort v228, v185, s[50:51]
	global_load_ushort v229, v177, s[50:51] offset:-2
	global_load_ushort v230, v181, s[50:51] offset:2
	v_add_u32_e32 v1, 0x600, v0
	v_cmp_lt_i32_e32 vcc, s7, v1
	s_or_b64 s[20:21], vcc, s[20:21]
	s_waitcnt vmcnt(0)
	v_cmp_eq_u32_e32 vcc, 0, v170
	v_cmp_eq_u32_e64 s[0:1], s5, v170
	v_lshlrev_b32_e32 v9, 16, v208
	v_lshlrev_b32_e32 v8, 16, v207
	v_lshlrev_b32_e32 v12, 16, v209
	v_cndmask_b32_e64 v8, v8, 0, vcc
	v_cndmask_b32_e64 v12, v12, 0, s[0:1]
	v_pk_mul_f32 v[8:9], v[2:3], v[8:9]
	v_lshlrev_b32_e32 v1, 16, v212
	v_add_f32_e32 v8, v8, v9
	v_fmac_f32_e32 v8, v6, v12
	v_add_f32_e32 v12, v7, v8
	v_lshlrev_b32_e32 v9, 16, v210
	v_lshlrev_b32_e32 v8, 16, v211
	v_cndmask_b32_e64 v1, v1, 0, s[0:1]
	v_cndmask_b32_e64 v8, v8, 0, vcc
	v_pk_mul_f32 v[8:9], v[2:3], v[8:9]
	s_nop 0
	v_add_f32_e32 v8, v8, v9
	v_fmac_f32_e32 v8, v6, v1
	v_add_f32_e32 v1, v7, v8
	v_cvt_pk_bf16_f32 v1, v12, v1
	global_store_dword v[4:5], v1, off
	v_cmp_eq_u32_e32 vcc, 0, v171
	v_cmp_eq_u32_e64 s[0:1], s5, v171
	v_lshlrev_b32_e32 v9, 16, v214
	v_lshlrev_b32_e32 v8, 16, v213
	v_lshlrev_b32_e32 v12, 16, v215
	v_cndmask_b32_e64 v8, v8, 0, vcc
	v_cndmask_b32_e64 v12, v12, 0, s[0:1]
	v_pk_mul_f32 v[8:9], v[2:3], v[8:9]
	v_lshlrev_b32_e32 v1, 16, v218
	v_add_f32_e32 v8, v8, v9
	v_fmac_f32_e32 v8, v6, v12
	v_add_f32_e32 v12, v7, v8
	v_lshlrev_b32_e32 v9, 16, v216
	v_lshlrev_b32_e32 v8, 16, v217
	v_cndmask_b32_e64 v1, v1, 0, s[0:1]
	v_cndmask_b32_e64 v8, v8, 0, vcc
	v_pk_mul_f32 v[8:9], v[2:3], v[8:9]
	s_nop 0
	v_add_f32_e32 v8, v8, v9
	v_fmac_f32_e32 v8, v6, v1
	v_add_f32_e32 v1, v7, v8
	v_cvt_pk_bf16_f32 v1, v12, v1
	global_store_dword v[4:5], v1, off offset:2048
	v_lshl_add_u64 v[4:5], v[4:5], 0, s[22:23]
	v_lshl_add_u64 v[4:5], v[4:5], 0, s[22:23]
	v_cmp_eq_u32_e32 vcc, 0, v172
	v_cmp_eq_u32_e64 s[0:1], s5, v172
	v_lshlrev_b32_e32 v9, 16, v220
	v_lshlrev_b32_e32 v8, 16, v219
	v_lshlrev_b32_e32 v12, 16, v221
	v_cndmask_b32_e64 v8, v8, 0, vcc
	v_cndmask_b32_e64 v12, v12, 0, s[0:1]
	v_pk_mul_f32 v[8:9], v[2:3], v[8:9]
	v_lshlrev_b32_e32 v1, 16, v224
	v_add_f32_e32 v8, v8, v9
	v_fmac_f32_e32 v8, v6, v12
	v_add_f32_e32 v12, v7, v8
	v_lshlrev_b32_e32 v9, 16, v222
	v_lshlrev_b32_e32 v8, 16, v223
	v_cndmask_b32_e64 v1, v1, 0, s[0:1]
	v_cndmask_b32_e64 v8, v8, 0, vcc
	v_pk_mul_f32 v[8:9], v[2:3], v[8:9]
	s_nop 0
	v_add_f32_e32 v8, v8, v9
	v_fmac_f32_e32 v8, v6, v1
	v_add_f32_e32 v1, v7, v8
	v_cvt_pk_bf16_f32 v1, v12, v1
	global_store_dword v[4:5], v1, off
	v_cmp_eq_u32_e32 vcc, 0, v173
	v_cmp_eq_u32_e64 s[0:1], s5, v173
	v_lshlrev_b32_e32 v9, 16, v226
	v_lshlrev_b32_e32 v8, 16, v225
	v_lshlrev_b32_e32 v12, 16, v227
	v_cndmask_b32_e64 v8, v8, 0, vcc
	v_cndmask_b32_e64 v12, v12, 0, s[0:1]
	v_pk_mul_f32 v[8:9], v[2:3], v[8:9]
	v_lshlrev_b32_e32 v1, 16, v230
	v_add_f32_e32 v8, v8, v9
	v_fmac_f32_e32 v8, v6, v12
	v_add_f32_e32 v12, v7, v8
	v_lshlrev_b32_e32 v9, 16, v228
	v_lshlrev_b32_e32 v8, 16, v229
	v_cndmask_b32_e64 v1, v1, 0, s[0:1]
	v_cndmask_b32_e64 v8, v8, 0, vcc
	v_pk_mul_f32 v[8:9], v[2:3], v[8:9]
	s_nop 0
	v_add_f32_e32 v8, v8, v9
	v_fmac_f32_e32 v8, v6, v1
	v_add_f32_e32 v1, v7, v8
	v_cvt_pk_bf16_f32 v1, v12, v1
	global_store_dword v[4:5], v1, off offset:2048
	v_lshl_add_u64 v[4:5], v[4:5], 0, s[22:23]
	v_lshl_add_u64 v[4:5], v[4:5], 0, s[22:23]
	v_add_u32_e32 v0, 0x800, v0
	s_andn2_b64 exec, exec, s[20:21]
	s_cbranch_execnz .LBB0_518

; __device__ __forceinline__ unsigned cvt_pk_bf16(float lo, float hi) { unsigned r; asm volatile("v_cvt_pk_bf16_f32 %0, %1, %2" : "=v"(r) : "v"(lo), "v"(hi)); return r; }
; __device__ __forceinline__ float bf2f(bf16_t b) { return __uint_as_float(((unsigned)b) << 16); }
; __device__ __forceinline__ float sconv(const bf16_t* row, int t, int L, float w0, float w1, float w2, float b) {
;   const int tm = t > 0 ? t - 1 : 0, tp = t + 1 < L ? t + 1 : L - 1;
;   const float vm = bf2f(row[tm]), p0 = bf2f(row[t]), vp = bf2f(row[tp]);
;   const float pm = t > 0 ? vm : 0.f, pp = t + 1 < L ? vp : 0.f;
;   return pm * w0 + p0 * w1 + pp * w2 + b;
; template <int LOGN, bool DUAL>
; __device__ void hyena_unit(const Params& p, unsigned char* shm, int ca, int cb, int ka, int kb) {
;     ...
;     const float w0a = cw[ca], w1a = cw[3072 + ca], w2a = cw[6144 + ca], bba = cb_[ca];
;     const float w0b = cw[cb], w1b = cw[3072 + cb], w2b = cw[6144 + cb], bbb = cb_[cb];
;     const bf16_t* r0 = hyT + (size_t)ca * L; const bf16_t* r1 = r0 + seqstride;
; #pragma unroll 4
;     for (int i = tid; i < LX; i += 512) {
;       const int ch = i >> LOGN, t = i & (L - 1);
;       const float w0 = ch ? w0b : w0a, w1 = ch ? w1b : w1a, w2 = ch ? w2b : w2a, bb = ch ? bbb : bba;
;       Wd[i] = cvt_pk_bf16(sconv(r0 + (size_t)ch * rowdiff, t, L, w0, w1, w2, bb), sconv(r1 + (size_t)ch * rowdiff, t, L, w0, w1, w2, bb));
;     }
.LBB0_944:
	v_ashrrev_i32_e32 v1, 13, v0
	v_mul_lo_u32 v186, v1, s84
	v_lshlrev_b32_e32 v186, 1, v186
	v_and_b32_e32 v170, 0x1fff, v0
	v_max_u32_e32 v174, 1, v170
	v_min_u32_e32 v178, 0x1ffe, v170
	v_lshl_add_u32 v182, v170, 1, v186
	v_lshl_add_u32 v174, v174, 1, v186
	v_lshl_add_u32 v178, v178, 1, v186
	v_add_u32_e32 v171, 0x200, v0
	v_and_b32_e32 v171, 0x1fff, v171
	v_max_u32_e32 v175, 1, v171
	v_min_u32_e32 v179, 0x1ffe, v171
	v_lshl_add_u32 v183, v171, 1, v186
	v_lshl_add_u32 v175, v175, 1, v186
	v_lshl_add_u32 v179, v179, 1, v186
	v_add_u32_e32 v172, 0x400, v0
	v_and_b32_e32 v172, 0x1fff, v172
	v_max_u32_e32 v176, 1, v172
	v_min_u32_e32 v180, 0x1ffe, v172
	v_lshl_add_u32 v184, v172, 1, v186
	v_lshl_add_u32 v176, v176, 1, v186
	v_lshl_add_u32 v180, v180, 1, v186
	v_add_u32_e32 v173, 0x600, v0
	v_and_b32_e32 v173, 0x1fff, v173
	v_max_u32_e32 v177, 1, v173
	v_min_u32_e32 v181, 0x1ffe, v173
	v_lshl_add_u32 v185, v173, 1, v186
	v_lshl_add_u32 v177, v177, 1, v186
	v_lshl_add_u32 v181, v181, 1, v186
	global_load_ushort v207, v174, s[44:45] offset:-2
	global_load_ushort v208, v182, s[44:45]
	global_load_ushort v209, v178, s[44:45] offset:2
	global_load_ushort v211, v174, s[46:47] offset:-2
	global_load_ushort v210, v182, s[46:47]
	global_load_ushort v212, v178, s[46:47] offset:2
	global_load_ushort v213, v175, s[44:45] offset:-2
	global_load_ushort v214, v183, s[44:45]
	global_load_ushort v215, v179, s[44:45] offset:2
	global_load_ushort v217, v175, s[46:47] offset:-2
	global_load_ushort v216, v183, s[46:47]
	global_load_ushort v218, v179, s[46:47] offset:2
	global_load_ushort v219, v176, s[44:45] offset:-2
	global_load_ushort v220, v184, s[44:45]
	global_load_ushort v221, v180, s[44:45] offset:2
	global_load_ushort v223, v176, s[46:47] offset:-2
	global_load_ushort v222, v184, s[46:47]
	global_load_ushort v224, v180, s[46:47] offset:2
	global_load_ushort v225, v177, s[44:45] offset:-2
	global_load_ushort v226, v185, s[44:45]
	global_load_ushort v227, v181, s[44:45] offset:2
	global_load_ushort v229, v177, s[46:47] offset:-2
	global_load_ushort v228, v185, s[46:47]
	global_load_ushort v230, v181, s[46:47] offset:2
	v_add_u32_e32 v1, 0x600, v0
	v_cmp_lt_i32_e32 vcc, s31, v1
	s_or_b64 s[36:37], vcc, s[36:37]
	v_mov_b32_e32 v187, 0x1fff
	v_cmp_gt_u32_e32 vcc, s70, v0
	s_nop 1
	s_waitcnt vmcnt(0)
	v_cndmask_b32_e32 v20, v8, v4, vcc
	v_cndmask_b32_e32 v21, v11, v5, vcc
	v_cndmask_b32_e32 v22, v10, v6, vcc
	v_cndmask_b32_e32 v23, v9, v7, vcc
	v_cmp_eq_u32_e32 vcc, 0, v170
	v_cmp_eq_u32_e64 s[0:1], v187, v170
	v_lshlrev_b32_e32 v1, 16, v207
	v_lshlrev_b32_e32 v25, 16, v208
	v_lshlrev_b32_e32 v14, 16, v209
	v_cndmask_b32_e64 v1, v1, 0, vcc
	v_mul_f32_e32 v15, v21, v25
	v_cndmask_b32_e64 v14, v14, 0, s[0:1]
	v_fmac_f32_e32 v15, v20, v1
	v_fmac_f32_e32 v15, v22, v14
	v_add_f32_e32 v1, v23, v15
	v_lshlrev_b32_e32 v24, 16, v211
	v_lshlrev_b32_e32 v14, 16, v210
	v_lshlrev_b32_e32 v12, 16, v212
	v_cndmask_b32_e64 v13, v24, 0, vcc
	v_mul_f32_e32 v14, v21, v14
	v_cndmask_b32_e64 v12, v12, 0, s[0:1]
	v_fmac_f32_e32 v14, v20, v13
	v_fmac_f32_e32 v14, v22, v12
	v_add_f32_e32 v12, v23, v14
	v_cvt_pk_bf16_f32 v1, v1, v12
	global_store_dword v[2:3], v1, off
	v_cmp_eq_u32_e32 vcc, 0, v171
	v_cmp_eq_u32_e64 s[0:1], v187, v171
	v_lshlrev_b32_e32 v1, 16, v213
	v_lshlrev_b32_e32 v25, 16, v214
	v_lshlrev_b32_e32 v14, 16, v215
	v_cndmask_b32_e64 v1, v1, 0, vcc
	v_mul_f32_e32 v15, v21, v25
	v_cndmask_b32_e64 v14, v14, 0, s[0:1]
	v_fmac_f32_e32 v15, v20, v1
	v_fmac_f32_e32 v15, v22, v14
	v_add_f32_e32 v1, v23, v15
	v_lshlrev_b32_e32 v24, 16, v217
	v_lshlrev_b32_e32 v14, 16, v216
	v_lshlrev_b32_e32 v12, 16, v218
	v_cndmask_b32_e64 v13, v24, 0, vcc
	v_mul_f32_e32 v14, v21, v14
	v_cndmask_b32_e64 v12, v12, 0, s[0:1]
	v_fmac_f32_e32 v14, v20, v13
	v_fmac_f32_e32 v14, v22, v12
	v_add_f32_e32 v12, v23, v14
	v_cvt_pk_bf16_f32 v1, v1, v12
	global_store_dword v[2:3], v1, off offset:2048
	v_lshl_add_u64 v[2:3], v[2:3], 0, s[40:41]
	v_lshl_add_u64 v[2:3], v[2:3], 0, s[40:41]
	v_cmp_eq_u32_e32 vcc, 0, v172
	v_cmp_eq_u32_e64 s[0:1], v187, v172
	v_lshlrev_b32_e32 v1, 16, v219
	v_lshlrev_b32_e32 v25, 16, v220
	v_lshlrev_b32_e32 v14, 16, v221
	v_cndmask_b32_e64 v1, v1, 0, vcc
	v_mul_f32_e32 v15, v21, v25
	v_cndmask_b32_e64 v14, v14, 0, s[0:1]
	v_fmac_f32_e32 v15, v20, v1
	v_fmac_f32_e32 v15, v22, v14
	v_add_f32_e32 v1, v23, v15
	v_lshlrev_b32_e32 v24, 16, v223
	v_lshlrev_b32_e32 v14, 16, v222
	v_lshlrev_b32_e32 v12, 16, v224
	v_cndmask_b32_e64 v13, v24, 0, vcc
	v_mul_f32_e32 v14, v21, v14
	v_cndmask_b32_e64 v12, v12, 0, s[0:1]
	v_fmac_f32_e32 v14, v20, v13
	v_fmac_f32_e32 v14, v22, v12
	v_add_f32_e32 v12, v23, v14
	v_cvt_pk_bf16_f32 v1, v1, v12
	global_store_dword v[2:3], v1, off
	v_cmp_eq_u32_e32 vcc, 0, v173
	v_cmp_eq_u32_e64 s[0:1], v187, v173
	v_lshlrev_b32_e32 v1, 16, v225
	v_lshlrev_b32_e32 v25, 16, v226
	v_lshlrev_b32_e32 v14, 16, v227
	v_cndmask_b32_e64 v1, v1, 0, vcc
	v_mul_f32_e32 v15, v21, v25
	v_cndmask_b32_e64 v14, v14, 0, s[0:1]
	v_fmac_f32_e32 v15, v20, v1
	v_fmac_f32_e32 v15, v22, v14
	v_add_f32_e32 v1, v23, v15
	v_lshlrev_b32_e32 v24, 16, v229
	v_lshlrev_b32_e32 v14, 16, v228
	v_lshlrev_b32_e32 v12, 16, v230
	v_cndmask_b32_e64 v13, v24, 0, vcc
	v_mul_f32_e32 v14, v21, v14
	v_cndmask_b32_e64 v12, v12, 0, s[0:1]
	v_fmac_f32_e32 v14, v20, v13
	v_fmac_f32_e32 v14, v22, v12
	v_add_f32_e32 v12, v23, v14
	v_cvt_pk_bf16_f32 v1, v1, v12
	global_store_dword v[2:3], v1, off offset:2048
	v_lshl_add_u64 v[2:3], v[2:3], 0, s[40:41]
	v_lshl_add_u64 v[2:3], v[2:3], 0, s[40:41]
	v_add_u32_e32 v0, 0x800, v0
	s_andn2_b64 exec, exec, s[36:37]
	s_cbranch_execnz .LBB0_944

; __device__ void convert_wt(unsigned char* shm, const float* W, int K, int ldw, int c0, int ncols, bf16_t* Bt, int blk, int off) {
;     ...
;   for (int t = blockIdx.x; t < ntile; t += gridDim.x) {
;     const int kt = t % tk, nt_ = t / tk;
;     __syncthreads();
; #pragma unroll
;     for (int i = 0; i < 8; ++i) { const int e = tid + i * 512, r = e >> 6, c = e & 63; tile[r * 65 + c] = W[(size_t)(kt * 64 + r) * ldw + c0 + nt_ * 64 + c]; }
.LBB0_1253:
	s_ashr_i32 s0, s5, 31
	s_lshr_b32 s0, s0, 27
	s_add_i32 s7, s5, s0
	s_ashr_i32 s11, s7, 5
	s_lshl_b32 s0, s11, 6
	s_ashr_i32 s1, s0, 31
	v_lshl_add_u64 v[28:29], s[0:1], 2, v[0:1]
	s_lshl_b32 s1, s11, 11
	s_sub_i32 s1, s17, s1
	v_add_u32_e32 v3, s1, v5
	v_mad_i64_i32 v[30:31], s[14:15], v3, s21, v[28:29]
	s_waitcnt lgkmcnt(0)
	s_barrier
	global_load_dword v230, v[30:31], off
	s_andn2_b32 s7, s7, 31
	v_add_u32_e32 v5, s57, v5


; __device__ void convert_wt(unsigned char* shm, const float* W, int K, int ldw, int c0, int ncols, bf16_t* Bt, int blk, int off) {
;     ...
;     for (int i = 0; i < 8; ++i) { const int e = tid + i * 512, r = e >> 6, c = e & 63; tile[r * 65 + c] = W[(size_t)(kt * 64 + r) * ldw + c0 + nt_ * 64 + c]; }
	v_add_u32_e32 v3, s1, v6
	v_mad_i64_i32 v[30:31], s[14:15], v3, s21, v[28:29]
	global_load_dword v231, v[30:31], off
	v_add_u32_e32 v6, s57, v6


; __device__ void convert_wt(unsigned char* shm, const float* W, int K, int ldw, int c0, int ncols, bf16_t* Bt, int blk, int off) {
;     ...
;     for (int i = 0; i < 8; ++i) { const int e = tid + i * 512, r = e >> 6, c = e & 63; tile[r * 65 + c] = W[(size_t)(kt * 64 + r) * ldw + c0 + nt_ * 64 + c]; }
	v_add_u32_e32 v3, s1, v7
	v_mad_i64_i32 v[30:31], s[14:15], v3, s21, v[28:29]
	global_load_dword v232, v[30:31], off
	v_add_u32_e32 v7, s57, v7


; __device__ void convert_wt(unsigned char* shm, const float* W, int K, int ldw, int c0, int ncols, bf16_t* Bt, int blk, int off) {
;     ...
;     for (int i = 0; i < 8; ++i) { const int e = tid + i * 512, r = e >> 6, c = e & 63; tile[r * 65 + c] = W[(size_t)(kt * 64 + r) * ldw + c0 + nt_ * 64 + c]; }
	v_add_u32_e32 v3, s1, v8
	v_mad_i64_i32 v[30:31], s[14:15], v3, s21, v[28:29]
	global_load_dword v233, v[30:31], off
	v_add_u32_e32 v8, s57, v8


; __device__ void convert_wt(unsigned char* shm, const float* W, int K, int ldw, int c0, int ncols, bf16_t* Bt, int blk, int off) {
;     ...
;     for (int i = 0; i < 8; ++i) { const int e = tid + i * 512, r = e >> 6, c = e & 63; tile[r * 65 + c] = W[(size_t)(kt * 64 + r) * ldw + c0 + nt_ * 64 + c]; }
	v_add_u32_e32 v3, s1, v9
	v_mad_i64_i32 v[30:31], s[14:15], v3, s21, v[28:29]
	global_load_dword v234, v[30:31], off
	v_add_u32_e32 v9, s57, v9


; __device__ void convert_wt(unsigned char* shm, const float* W, int K, int ldw, int c0, int ncols, bf16_t* Bt, int blk, int off) {
;     ...
;     for (int i = 0; i < 8; ++i) { const int e = tid + i * 512, r = e >> 6, c = e & 63; tile[r * 65 + c] = W[(size_t)(kt * 64 + r) * ldw + c0 + nt_ * 64 + c]; }
	v_add_u32_e32 v3, s1, v10
	v_mad_i64_i32 v[30:31], s[14:15], v3, s21, v[28:29]
	global_load_dword v235, v[30:31], off
	v_add_u32_e32 v10, s57, v10


; __device__ void convert_wt(unsigned char* shm, const float* W, int K, int ldw, int c0, int ncols, bf16_t* Bt, int blk, int off) {
;     ...
;     for (int i = 0; i < 8; ++i) { const int e = tid + i * 512, r = e >> 6, c = e & 63; tile[r * 65 + c] = W[(size_t)(kt * 64 + r) * ldw + c0 + nt_ * 64 + c]; }
	v_add_u32_e32 v3, s1, v11
	v_mad_i64_i32 v[30:31], s[14:15], v3, s21, v[28:29]
	global_load_dword v236, v[30:31], off
	v_add_u32_e32 v11, s57, v11


; __device__ void convert_wt(unsigned char* shm, const float* W, int K, int ldw, int c0, int ncols, bf16_t* Bt, int blk, int off) {
;     ...
;     for (int i = 0; i < 8; ++i) { const int e = tid + i * 512, r = e >> 6, c = e & 63; tile[r * 65 + c] = W[(size_t)(kt * 64 + r) * ldw + c0 + nt_ * 64 + c]; }
	v_add_u32_e32 v3, s1, v12
	v_mad_i64_i32 v[28:29], s[14:15], v3, s21, v[28:29]
	global_load_dword v237, v[28:29], off
	s_waitcnt vmcnt(0)
	ds_write_b32 v20, v230
	ds_write_b32 v21, v231
	ds_write_b32 v22, v232
	ds_write_b32 v23, v233
	ds_write_b32 v24, v234
	ds_write_b32 v25, v235
	ds_write_b32 v26, v236
	ds_write_b32 v27, v237
	v_add_u32_e32 v12, s57, v12


; __device__ __forceinline__ unsigned cvt_pk_bf16(float lo, float hi) { unsigned r; asm volatile("v_cvt_pk_bf16_f32 %0, %1, %2" : "=v"(r) : "v"(lo), "v"(hi)); return r; }
; __device__ void convert_wt(unsigned char* shm, const float* W, int K, int ldw, int c0, int ncols, bf16_t* Bt, int blk, int off) {
;     ...
;     __syncthreads();
; #pragma unroll
;     for (int i = 0; i < 4; ++i) { const int e = tid + i * 512, n = e >> 5, kp = (e & 31) * 2; const int c = nt_ * 64 + n;
;       const unsigned w = cvt_pk_bf16(tile[kp * 65 + n], tile[(kp + 1) * 65 + n]);
;       const int nr = (c >> 7) * blk + off + (c & 127);
;       *(unsigned*)(Bt + ((size_t)((nr >> 8) * tk + kt) * 256 + (nr & 255)) * 64 + kp) = w; }
	s_waitcnt lgkmcnt(0)
	s_barrier
	v_add_u32_e32 v3, s0, v4
	ds_read2_b32 v[28:29], v13 offset1:65
	s_waitcnt lgkmcnt(0)
	v_cvt_pk_bf16_f32 v30, v28, v29
	v_ashrrev_i32_e32 v28, 3, v3
	v_and_b32_e32 v28, 0xffffffe0, v28
	v_subrev_u32_e32 v28, s7, v28
	v_add_u32_e32 v28, s5, v28
	v_ashrrev_i32_e32 v29, 31, v28
	v_lshlrev_b64 v[28:29], 15, v[28:29]
	v_lshlrev_b32_e32 v3, 7, v3
	v_lshl_add_u64 v[28:29], s[24:25], 0, v[28:29]
	v_and_b32_e32 v32, 0x7f80, v3
	v_lshl_add_u64 v[28:29], v[28:29], 0, v[32:33]
	v_mov_b32_e32 v3, v33
	v_lshl_add_u64 v[28:29], v[28:29], 0, v[2:3]
	global_store_dword v[28:29], v30, off
	v_add_u32_e32 v30, s0, v14
	ds_read2_b32 v[28:29], v15 offset1:65
	s_waitcnt lgkmcnt(0)
	v_cvt_pk_bf16_f32 v31, v28, v29
	v_ashrrev_i32_e32 v28, 3, v30
	v_and_b32_e32 v28, 0xffffffe0, v28
	v_subrev_u32_e32 v28, s7, v28
	v_add_u32_e32 v28, s5, v28
	v_ashrrev_i32_e32 v29, 31, v28
	v_lshlrev_b64 v[28:29], 15, v[28:29]
	v_lshlrev_b32_e32 v30, 7, v30
	v_lshl_add_u64 v[28:29], s[24:25], 0, v[28:29]
	v_and_b32_e32 v32, 0x7f80, v30
	v_lshl_add_u64 v[28:29], v[28:29], 0, v[32:33]
	v_lshl_add_u64 v[28:29], v[28:29], 0, v[2:3]
	global_store_dword v[28:29], v31, off
	v_add_u32_e32 v30, s0, v16
	ds_read2_b32 v[28:29], v17 offset1:65
	s_waitcnt lgkmcnt(0)
	v_cvt_pk_bf16_f32 v31, v28, v29
	v_ashrrev_i32_e32 v28, 3, v30
	v_and_b32_e32 v28, 0xffffffe0, v28
	v_subrev_u32_e32 v28, s7, v28
	v_add_u32_e32 v28, s5, v28
	v_ashrrev_i32_e32 v29, 31, v28
	v_lshlrev_b64 v[28:29], 15, v[28:29]
	v_lshlrev_b32_e32 v30, 7, v30
	v_lshl_add_u64 v[28:29], s[24:25], 0, v[28:29]
	v_and_b32_e32 v32, 0x7f80, v30
	v_lshl_add_u64 v[28:29], v[28:29], 0, v[32:33]
	v_lshl_add_u64 v[28:29], v[28:29], 0, v[2:3]
	global_store_dword v[28:29], v31, off
	v_add_u32_e32 v30, s0, v18
	ds_read2_b32 v[28:29], v19 offset1:65
	s_waitcnt lgkmcnt(0)
	v_cvt_pk_bf16_f32 v31, v28, v29
	v_ashrrev_i32_e32 v28, 3, v30
	v_and_b32_e32 v28, 0xffffffe0, v28
	v_subrev_u32_e32 v28, s7, v28
	v_add_u32_e32 v28, s5, v28
	v_ashrrev_i32_e32 v29, 31, v28
	v_lshlrev_b64 v[28:29], 15, v[28:29]
	v_lshlrev_b32_e32 v30, 7, v30
	v_lshl_add_u64 v[28:29], s[24:25], 0, v[28:29]
	v_and_b32_e32 v32, 0x7f80, v30
	v_lshl_add_u64 v[28:29], v[28:29], 0, v[32:33]
	s_add_i32 s5, s5, s20
	v_lshl_add_u64 v[28:29], v[28:29], 0, v[2:3]
	s_cmpk_lt_i32 s5, 0xf00
	global_store_dword v[28:29], v31, off
	s_cbranch_scc1 .LBB0_1253

; __device__ void convert_wt(unsigned char* shm, const float* W, int K, int ldw, int c0, int ncols, bf16_t* Bt, int blk, int off) {
;     ...
;   for (int t = blockIdx.x; t < ntile; t += gridDim.x) {
;     const int kt = t % tk, nt_ = t / tk;
;     __syncthreads();
; #pragma unroll
;     for (int i = 0; i < 8; ++i) { const int e = tid + i * 512, r = e >> 6, c = e & 63; tile[r * 65 + c] = W[(size_t)(kt * 64 + r) * ldw + c0 + nt_ * 64 + c]; }
.LBB0_1256:
	s_ashr_i32 s0, s5, 31
	s_lshr_b32 s0, s0, 27
	s_add_i32 s7, s5, s0
	s_ashr_i32 s11, s7, 5
	s_lshl_b32 s0, s11, 6
	s_ashr_i32 s1, s0, 31
	v_lshl_add_u64 v[28:29], s[0:1], 2, v[0:1]
	s_lshl_b32 s1, s11, 11
	s_sub_i32 s1, s17, s1
	v_add_u32_e32 v3, s1, v5
	v_mad_i64_i32 v[30:31], s[14:15], v3, s21, v[28:29]
	s_barrier
	global_load_dword v230, v[30:31], off
	s_andn2_b32 s7, s7, 31
	v_add_u32_e32 v5, s57, v5


; __device__ void convert_wt(unsigned char* shm, const float* W, int K, int ldw, int c0, int ncols, bf16_t* Bt, int blk, int off) {
;     ...
;     for (int i = 0; i < 8; ++i) { const int e = tid + i * 512, r = e >> 6, c = e & 63; tile[r * 65 + c] = W[(size_t)(kt * 64 + r) * ldw + c0 + nt_ * 64 + c]; }
	v_add_u32_e32 v3, s1, v6
	v_mad_i64_i32 v[30:31], s[14:15], v3, s21, v[28:29]
	global_load_dword v231, v[30:31], off
	v_add_u32_e32 v6, s57, v6


; __device__ void convert_wt(unsigned char* shm, const float* W, int K, int ldw, int c0, int ncols, bf16_t* Bt, int blk, int off) {
;     ...
;     for (int i = 0; i < 8; ++i) { const int e = tid + i * 512, r = e >> 6, c = e & 63; tile[r * 65 + c] = W[(size_t)(kt * 64 + r) * ldw + c0 + nt_ * 64 + c]; }
	v_add_u32_e32 v3, s1, v7
	v_mad_i64_i32 v[30:31], s[14:15], v3, s21, v[28:29]
	global_load_dword v232, v[30:31], off
	v_add_u32_e32 v7, s57, v7


; __device__ void convert_wt(unsigned char* shm, const float* W, int K, int ldw, int c0, int ncols, bf16_t* Bt, int blk, int off) {
;     ...
;     for (int i = 0; i < 8; ++i) { const int e = tid + i * 512, r = e >> 6, c = e & 63; tile[r * 65 + c] = W[(size_t)(kt * 64 + r) * ldw + c0 + nt_ * 64 + c]; }
	v_add_u32_e32 v3, s1, v8
	v_mad_i64_i32 v[30:31], s[14:15], v3, s21, v[28:29]
	global_load_dword v233, v[30:31], off
	v_add_u32_e32 v8, s57, v8


; __device__ void convert_wt(unsigned char* shm, const float* W, int K, int ldw, int c0, int ncols, bf16_t* Bt, int blk, int off) {
;     ...
;     for (int i = 0; i < 8; ++i) { const int e = tid + i * 512, r = e >> 6, c = e & 63; tile[r * 65 + c] = W[(size_t)(kt * 64 + r) * ldw + c0 + nt_ * 64 + c]; }
	v_add_u32_e32 v3, s1, v9
	v_mad_i64_i32 v[30:31], s[14:15], v3, s21, v[28:29]
	global_load_dword v234, v[30:31], off
	v_add_u32_e32 v9, s57, v9


; __device__ void convert_wt(unsigned char* shm, const float* W, int K, int ldw, int c0, int ncols, bf16_t* Bt, int blk, int off) {
;     ...
;     for (int i = 0; i < 8; ++i) { const int e = tid + i * 512, r = e >> 6, c = e & 63; tile[r * 65 + c] = W[(size_t)(kt * 64 + r) * ldw + c0 + nt_ * 64 + c]; }
	v_add_u32_e32 v3, s1, v10
	v_mad_i64_i32 v[30:31], s[14:15], v3, s21, v[28:29]
	global_load_dword v235, v[30:31], off
	v_add_u32_e32 v10, s57, v10


; __device__ void convert_wt(unsigned char* shm, const float* W, int K, int ldw, int c0, int ncols, bf16_t* Bt, int blk, int off) {
;     ...
;     for (int i = 0; i < 8; ++i) { const int e = tid + i * 512, r = e >> 6, c = e & 63; tile[r * 65 + c] = W[(size_t)(kt * 64 + r) * ldw + c0 + nt_ * 64 + c]; }
	v_add_u32_e32 v3, s1, v11
	v_mad_i64_i32 v[30:31], s[14:15], v3, s21, v[28:29]
	global_load_dword v236, v[30:31], off
	v_add_u32_e32 v11, s57, v11


; __device__ void convert_wt(unsigned char* shm, const float* W, int K, int ldw, int c0, int ncols, bf16_t* Bt, int blk, int off) {
;     ...
;     for (int i = 0; i < 8; ++i) { const int e = tid + i * 512, r = e >> 6, c = e & 63; tile[r * 65 + c] = W[(size_t)(kt * 64 + r) * ldw + c0 + nt_ * 64 + c]; }
	v_add_u32_e32 v3, s1, v12
	v_mad_i64_i32 v[28:29], s[14:15], v3, s21, v[28:29]
	global_load_dword v237, v[28:29], off
	s_waitcnt vmcnt(0)
	ds_write_b32 v20, v230
	ds_write_b32 v21, v231
	ds_write_b32 v22, v232
	ds_write_b32 v23, v233
	ds_write_b32 v24, v234
	ds_write_b32 v25, v235
	ds_write_b32 v26, v236
	ds_write_b32 v27, v237
	v_add_u32_e32 v12, s57, v12


; __device__ __forceinline__ unsigned cvt_pk_bf16(float lo, float hi) { unsigned r; asm volatile("v_cvt_pk_bf16_f32 %0, %1, %2" : "=v"(r) : "v"(lo), "v"(hi)); return r; }
; __device__ void convert_wt(unsigned char* shm, const float* W, int K, int ldw, int c0, int ncols, bf16_t* Bt, int blk, int off) {
;     ...
;     __syncthreads();
; #pragma unroll
;     for (int i = 0; i < 4; ++i) { const int e = tid + i * 512, n = e >> 5, kp = (e & 31) * 2; const int c = nt_ * 64 + n;
;       const unsigned w = cvt_pk_bf16(tile[kp * 65 + n], tile[(kp + 1) * 65 + n]);
;       const int nr = (c >> 7) * blk + off + (c & 127);
;       *(unsigned*)(Bt + ((size_t)((nr >> 8) * tk + kt) * 256 + (nr & 255)) * 64 + kp) = w; }
	s_waitcnt lgkmcnt(0)
	s_barrier
	v_add_u32_e32 v3, s0, v4
	ds_read2_b32 v[28:29], v13 offset1:65
	s_waitcnt lgkmcnt(0)
	v_cvt_pk_bf16_f32 v30, v28, v29
	v_ashrrev_i32_e32 v28, 2, v3
	v_and_b32_e32 v28, 0xffffffe0, v28
	v_subrev_u32_e32 v28, s7, v28
	v_add_u32_e32 v28, s5, v28
	v_ashrrev_i32_e32 v29, 31, v28
	v_lshlrev_b64 v[28:29], 15, v[28:29]
	v_lshlrev_b32_e32 v3, 7, v3
	v_lshl_add_u64 v[28:29], s[22:23], 0, v[28:29]
	v_and_b32_e32 v32, 0x3f80, v3
	v_lshl_add_u64 v[28:29], v[28:29], 0, v[32:33]
	v_mov_b32_e32 v3, v33
	v_lshl_add_u64 v[28:29], v[28:29], 0, v[2:3]
	global_store_dword v[28:29], v30, off
	v_add_u32_e32 v30, s0, v14
	ds_read2_b32 v[28:29], v15 offset1:65
	s_waitcnt lgkmcnt(0)
	v_cvt_pk_bf16_f32 v31, v28, v29
	v_ashrrev_i32_e32 v28, 2, v30
	v_and_b32_e32 v28, 0xffffffe0, v28
	v_subrev_u32_e32 v28, s7, v28
	v_add_u32_e32 v28, s5, v28
	v_ashrrev_i32_e32 v29, 31, v28
	v_lshlrev_b64 v[28:29], 15, v[28:29]
	v_lshlrev_b32_e32 v30, 7, v30
	v_lshl_add_u64 v[28:29], s[22:23], 0, v[28:29]
	v_and_b32_e32 v32, 0x3f80, v30
	v_lshl_add_u64 v[28:29], v[28:29], 0, v[32:33]
	v_lshl_add_u64 v[28:29], v[28:29], 0, v[2:3]
	global_store_dword v[28:29], v31, off
	v_add_u32_e32 v30, s0, v16
	ds_read2_b32 v[28:29], v17 offset1:65
	s_waitcnt lgkmcnt(0)
	v_cvt_pk_bf16_f32 v31, v28, v29
	v_ashrrev_i32_e32 v28, 2, v30
	v_and_b32_e32 v28, 0xffffffe0, v28
	v_subrev_u32_e32 v28, s7, v28
	v_add_u32_e32 v28, s5, v28
	v_ashrrev_i32_e32 v29, 31, v28
	v_lshlrev_b64 v[28:29], 15, v[28:29]
	v_lshlrev_b32_e32 v30, 7, v30
	v_lshl_add_u64 v[28:29], s[22:23], 0, v[28:29]
	v_and_b32_e32 v32, 0x3f80, v30
	v_lshl_add_u64 v[28:29], v[28:29], 0, v[32:33]
	v_lshl_add_u64 v[28:29], v[28:29], 0, v[2:3]
	global_store_dword v[28:29], v31, off
	v_add_u32_e32 v30, s0, v18
	ds_read2_b32 v[28:29], v19 offset1:65
	s_waitcnt lgkmcnt(0)
	v_cvt_pk_bf16_f32 v31, v28, v29
	v_ashrrev_i32_e32 v28, 2, v30
	v_and_b32_e32 v28, 0xffffffe0, v28
	v_subrev_u32_e32 v28, s7, v28
	v_add_u32_e32 v28, s5, v28
	v_ashrrev_i32_e32 v29, 31, v28
	v_lshlrev_b64 v[28:29], 15, v[28:29]
	v_lshlrev_b32_e32 v30, 7, v30
	v_lshl_add_u64 v[28:29], s[22:23], 0, v[28:29]
	v_and_b32_e32 v32, 0x3f80, v30
	v_lshl_add_u64 v[28:29], v[28:29], 0, v[32:33]
	s_add_i32 s5, s5, s20
	v_lshl_add_u64 v[28:29], v[28:29], 0, v[2:3]
	s_cmpk_lt_i32 s5, 0x400
	global_store_dword v[28:29], v31, off
	s_cbranch_scc1 .LBB0_1256

; __device__ void convert_wt(unsigned char* shm, const float* W, int K, int ldw, int c0, int ncols, bf16_t* Bt, int blk, int off) {
;     ...
;   for (int t = blockIdx.x; t < ntile; t += gridDim.x) {
;     const int kt = t % tk, nt_ = t / tk;
;     __syncthreads();
; #pragma unroll
;     for (int i = 0; i < 8; ++i) { const int e = tid + i * 512, r = e >> 6, c = e & 63; tile[r * 65 + c] = W[(size_t)(kt * 64 + r) * ldw + c0 + nt_ * 64 + c]; }
.LBB0_1262:
	s_ashr_i32 s0, s5, 31
	s_lshr_b32 s0, s0, 28
	s_add_i32 s0, s5, s0
	s_ashr_i32 s11, s0, 4
	s_and_b32 s7, s0, -16
	s_lshl_b32 s0, s11, 6
	s_ashr_i32 s1, s0, 31
	v_lshl_add_u64 v[4:5], s[0:1], 2, v[0:1]
	s_lshl_b32 s1, s11, 10
	s_sub_i32 s1, s17, s1
	v_add_u32_e32 v30, s1, v7
	v_ashrrev_i32_e32 v31, 31, v30
	v_lshlrev_b64 v[30:31], 13, v[30:31]
	v_lshl_add_u64 v[30:31], v[4:5], 0, v[30:31]
	s_barrier
	global_load_dword v230, v[30:31], off
	v_add_u32_e32 v30, s1, v8
	v_ashrrev_i32_e32 v31, 31, v30
	v_lshlrev_b64 v[30:31], 13, v[30:31]
	v_lshl_add_u64 v[30:31], v[4:5], 0, v[30:31]
	v_add_u32_e32 v8, s57, v8
	v_add_u32_e32 v7, s57, v7


; __device__ void convert_wt(unsigned char* shm, const float* W, int K, int ldw, int c0, int ncols, bf16_t* Bt, int blk, int off) {
;     ...
;     for (int i = 0; i < 8; ++i) { const int e = tid + i * 512, r = e >> 6, c = e & 63; tile[r * 65 + c] = W[(size_t)(kt * 64 + r) * ldw + c0 + nt_ * 64 + c]; }
	global_load_dword v231, v[30:31], off
	v_add_u32_e32 v30, s1, v9
	v_ashrrev_i32_e32 v31, 31, v30
	v_lshlrev_b64 v[30:31], 13, v[30:31]
	v_lshl_add_u64 v[30:31], v[4:5], 0, v[30:31]
	v_add_u32_e32 v9, s57, v9


; __device__ void convert_wt(unsigned char* shm, const float* W, int K, int ldw, int c0, int ncols, bf16_t* Bt, int blk, int off) {
;     ...
;     for (int i = 0; i < 8; ++i) { const int e = tid + i * 512, r = e >> 6, c = e & 63; tile[r * 65 + c] = W[(size_t)(kt * 64 + r) * ldw + c0 + nt_ * 64 + c]; }
	global_load_dword v232, v[30:31], off
	v_add_u32_e32 v30, s1, v10
	v_ashrrev_i32_e32 v31, 31, v30
	v_lshlrev_b64 v[30:31], 13, v[30:31]
	v_lshl_add_u64 v[30:31], v[4:5], 0, v[30:31]
	v_add_u32_e32 v10, s57, v10


; __device__ void convert_wt(unsigned char* shm, const float* W, int K, int ldw, int c0, int ncols, bf16_t* Bt, int blk, int off) {
;     ...
;     for (int i = 0; i < 8; ++i) { const int e = tid + i * 512, r = e >> 6, c = e & 63; tile[r * 65 + c] = W[(size_t)(kt * 64 + r) * ldw + c0 + nt_ * 64 + c]; }
	global_load_dword v233, v[30:31], off
	v_add_u32_e32 v30, s1, v11
	v_ashrrev_i32_e32 v31, 31, v30
	v_lshlrev_b64 v[30:31], 13, v[30:31]
	v_lshl_add_u64 v[30:31], v[4:5], 0, v[30:31]
	v_add_u32_e32 v11, s57, v11


; __device__ void convert_wt(unsigned char* shm, const float* W, int K, int ldw, int c0, int ncols, bf16_t* Bt, int blk, int off) {
;     ...
;     for (int i = 0; i < 8; ++i) { const int e = tid + i * 512, r = e >> 6, c = e & 63; tile[r * 65 + c] = W[(size_t)(kt * 64 + r) * ldw + c0 + nt_ * 64 + c]; }
	global_load_dword v234, v[30:31], off
	v_add_u32_e32 v30, s1, v12
	v_ashrrev_i32_e32 v31, 31, v30
	v_lshlrev_b64 v[30:31], 13, v[30:31]
	v_lshl_add_u64 v[30:31], v[4:5], 0, v[30:31]
	v_add_u32_e32 v12, s57, v12


; __device__ void convert_wt(unsigned char* shm, const float* W, int K, int ldw, int c0, int ncols, bf16_t* Bt, int blk, int off) {
;     ...
;     for (int i = 0; i < 8; ++i) { const int e = tid + i * 512, r = e >> 6, c = e & 63; tile[r * 65 + c] = W[(size_t)(kt * 64 + r) * ldw + c0 + nt_ * 64 + c]; }
	global_load_dword v235, v[30:31], off
	v_add_u32_e32 v30, s1, v13
	v_ashrrev_i32_e32 v31, 31, v30
	v_lshlrev_b64 v[30:31], 13, v[30:31]
	v_lshl_add_u64 v[30:31], v[4:5], 0, v[30:31]
	v_add_u32_e32 v13, s57, v13


; __device__ void convert_wt(unsigned char* shm, const float* W, int K, int ldw, int c0, int ncols, bf16_t* Bt, int blk, int off) {
;     ...
;     for (int i = 0; i < 8; ++i) { const int e = tid + i * 512, r = e >> 6, c = e & 63; tile[r * 65 + c] = W[(size_t)(kt * 64 + r) * ldw + c0 + nt_ * 64 + c]; }
	global_load_dword v236, v[30:31], off
	v_add_u32_e32 v30, s1, v14
	v_ashrrev_i32_e32 v31, 31, v30
	v_lshlrev_b64 v[30:31], 13, v[30:31]
	v_lshl_add_u64 v[4:5], v[4:5], 0, v[30:31]
	v_add_u32_e32 v14, s57, v14


; __device__ void convert_wt(unsigned char* shm, const float* W, int K, int ldw, int c0, int ncols, bf16_t* Bt, int blk, int off) {
;     ...
;     for (int i = 0; i < 8; ++i) { const int e = tid + i * 512, r = e >> 6, c = e & 63; tile[r * 65 + c] = W[(size_t)(kt * 64 + r) * ldw + c0 + nt_ * 64 + c]; }
	global_load_dword v237, v[4:5], off
	s_waitcnt vmcnt(0)
	ds_write_b32 v22, v230
	ds_write_b32 v23, v231
	ds_write_b32 v24, v232
	ds_write_b32 v25, v233
	ds_write_b32 v26, v234
	ds_write_b32 v27, v235
	ds_write_b32 v28, v236
	ds_write_b32 v29, v237


; __device__ __forceinline__ unsigned cvt_pk_bf16(float lo, float hi) { unsigned r; asm volatile("v_cvt_pk_bf16_f32 %0, %1, %2" : "=v"(r) : "v"(lo), "v"(hi)); return r; }
; __device__ void convert_wt(unsigned char* shm, const float* W, int K, int ldw, int c0, int ncols, bf16_t* Bt, int blk, int off) {
;     ...
;     __syncthreads();
; #pragma unroll
;     for (int i = 0; i < 4; ++i) { const int e = tid + i * 512, n = e >> 5, kp = (e & 31) * 2; const int c = nt_ * 64 + n;
;       const unsigned w = cvt_pk_bf16(tile[kp * 65 + n], tile[(kp + 1) * 65 + n]);
;       const int nr = (c >> 7) * blk + off + (c & 127);
;       *(unsigned*)(Bt + ((size_t)((nr >> 8) * tk + kt) * 256 + (nr & 255)) * 64 + kp) = w; }
	s_waitcnt lgkmcnt(0)
	s_barrier
	v_add_u32_e32 v3, s0, v6
	ds_read2_b32 v[4:5], v15 offset1:65
	s_waitcnt lgkmcnt(0)
	v_cvt_pk_bf16_f32 v30, v4, v5
	v_ashrrev_i32_e32 v4, 4, v3
	v_and_b32_e32 v4, -16, v4
	v_subrev_u32_e32 v4, s7, v4
	v_add_u32_e32 v4, s5, v4
	v_ashrrev_i32_e32 v5, 31, v4
	v_lshlrev_b64 v[4:5], 15, v[4:5]
	v_lshlrev_b32_e32 v3, 7, v3
	v_lshl_add_u64 v[4:5], s[20:21], 0, v[4:5]
	v_and_b32_e32 v32, 0x7f80, v3
	v_lshl_add_u64 v[4:5], v[4:5], 0, v[32:33]
	v_mov_b32_e32 v3, v33
	v_lshl_add_u64 v[4:5], v[4:5], 0, v[2:3]
	global_store_dword v[4:5], v30, off
	v_add_u32_e32 v30, s0, v16
	ds_read2_b32 v[4:5], v17 offset1:65
	s_waitcnt lgkmcnt(0)
	v_cvt_pk_bf16_f32 v31, v4, v5
	v_ashrrev_i32_e32 v4, 4, v30
	v_and_b32_e32 v4, -16, v4
	v_subrev_u32_e32 v4, s7, v4
	v_add_u32_e32 v4, s5, v4
	v_ashrrev_i32_e32 v5, 31, v4
	v_lshlrev_b64 v[4:5], 15, v[4:5]
	v_lshlrev_b32_e32 v30, 7, v30
	v_lshl_add_u64 v[4:5], s[20:21], 0, v[4:5]
	v_and_b32_e32 v32, 0x7f80, v30
	v_lshl_add_u64 v[4:5], v[4:5], 0, v[32:33]
	v_lshl_add_u64 v[4:5], v[4:5], 0, v[2:3]
	global_store_dword v[4:5], v31, off
	v_add_u32_e32 v30, s0, v18
	ds_read2_b32 v[4:5], v19 offset1:65
	s_waitcnt lgkmcnt(0)
	v_cvt_pk_bf16_f32 v31, v4, v5
	v_ashrrev_i32_e32 v4, 4, v30
	v_and_b32_e32 v4, -16, v4
	v_subrev_u32_e32 v4, s7, v4
	v_add_u32_e32 v4, s5, v4
	v_ashrrev_i32_e32 v5, 31, v4
	v_lshlrev_b64 v[4:5], 15, v[4:5]
	v_lshlrev_b32_e32 v30, 7, v30
	v_lshl_add_u64 v[4:5], s[20:21], 0, v[4:5]
	v_and_b32_e32 v32, 0x7f80, v30
	v_lshl_add_u64 v[4:5], v[4:5], 0, v[32:33]
	v_lshl_add_u64 v[4:5], v[4:5], 0, v[2:3]
	global_store_dword v[4:5], v31, off
	v_add_u32_e32 v30, s0, v20
	ds_read2_b32 v[4:5], v21 offset1:65
	s_waitcnt lgkmcnt(0)
	v_cvt_pk_bf16_f32 v31, v4, v5
	v_ashrrev_i32_e32 v4, 4, v30
	v_and_b32_e32 v4, -16, v4
	v_subrev_u32_e32 v4, s7, v4
	v_add_u32_e32 v4, s5, v4
	v_ashrrev_i32_e32 v5, 31, v4
	v_lshlrev_b64 v[4:5], 15, v[4:5]
	v_lshlrev_b32_e32 v30, 7, v30
	v_lshl_add_u64 v[4:5], s[20:21], 0, v[4:5]
	v_and_b32_e32 v32, 0x7f80, v30
	v_lshl_add_u64 v[4:5], v[4:5], 0, v[32:33]
	s_add_i32 s5, s5, s14
	v_lshl_add_u64 v[4:5], v[4:5], 0, v[2:3]
	s_cmpk_lt_i32 s5, 0x200
	global_store_dword v[4:5], v31, off
	s_cbranch_scc1 .LBB0_1262
	s_movk_i32 s64, 0x5800

; __device__ void convert_wt(unsigned char* shm, const float* W, int K, int ldw, int c0, int ncols, bf16_t* Bt, int blk, int off) {
;     ...
;   for (int t = blockIdx.x; t < ntile; t += gridDim.x) {
;     const int kt = t % tk, nt_ = t / tk;
;     __syncthreads();
; #pragma unroll
;     for (int i = 0; i < 8; ++i) { const int e = tid + i * 512, r = e >> 6, c = e & 63; tile[r * 65 + c] = W[(size_t)(kt * 64 + r) * ldw + c0 + nt_ * 64 + c]; }
.LBB0_1266:
	s_ashr_i32 s0, s5, 31
	s_lshr_b32 s0, s0, 29
	s_add_i32 s0, s5, s0
	s_ashr_i32 s11, s0, 3
	s_and_b32 s7, s0, -8
	s_lshl_b32 s0, s11, 6
	s_ashr_i32 s1, s0, 31
	v_lshl_add_u64 v[4:5], s[0:1], 2, v[0:1]
	s_lshl_b32 s1, s11, 9
	s_sub_i32 s1, s17, s1
	v_add_u32_e32 v30, s1, v7
	v_ashrrev_i32_e32 v31, 31, v30
	v_lshlrev_b64 v[30:31], 13, v[30:31]
	v_lshl_add_u64 v[30:31], v[4:5], 0, v[30:31]
	s_barrier
	global_load_dword v230, v[30:31], off
	v_add_u32_e32 v30, s1, v8
	v_ashrrev_i32_e32 v31, 31, v30
	v_lshlrev_b64 v[30:31], 13, v[30:31]
	v_lshl_add_u64 v[30:31], v[4:5], 0, v[30:31]
	v_add_u32_e32 v8, s57, v8
	v_add_u32_e32 v7, s57, v7


; __device__ void convert_wt(unsigned char* shm, const float* W, int K, int ldw, int c0, int ncols, bf16_t* Bt, int blk, int off) {
;     ...
;     for (int i = 0; i < 8; ++i) { const int e = tid + i * 512, r = e >> 6, c = e & 63; tile[r * 65 + c] = W[(size_t)(kt * 64 + r) * ldw + c0 + nt_ * 64 + c]; }
	global_load_dword v231, v[30:31], off
	v_add_u32_e32 v30, s1, v9
	v_ashrrev_i32_e32 v31, 31, v30
	v_lshlrev_b64 v[30:31], 13, v[30:31]
	v_lshl_add_u64 v[30:31], v[4:5], 0, v[30:31]
	v_add_u32_e32 v9, s57, v9


; __device__ void convert_wt(unsigned char* shm, const float* W, int K, int ldw, int c0, int ncols, bf16_t* Bt, int blk, int off) {
;     ...
;     for (int i = 0; i < 8; ++i) { const int e = tid + i * 512, r = e >> 6, c = e & 63; tile[r * 65 + c] = W[(size_t)(kt * 64 + r) * ldw + c0 + nt_ * 64 + c]; }
	global_load_dword v232, v[30:31], off
	v_add_u32_e32 v30, s1, v10
	v_ashrrev_i32_e32 v31, 31, v30
	v_lshlrev_b64 v[30:31], 13, v[30:31]
	v_lshl_add_u64 v[30:31], v[4:5], 0, v[30:31]
	v_add_u32_e32 v10, s57, v10


; __device__ void convert_wt(unsigned char* shm, const float* W, int K, int ldw, int c0, int ncols, bf16_t* Bt, int blk, int off) {
;     ...
;     for (int i = 0; i < 8; ++i) { const int e = tid + i * 512, r = e >> 6, c = e & 63; tile[r * 65 + c] = W[(size_t)(kt * 64 + r) * ldw + c0 + nt_ * 64 + c]; }
	global_load_dword v233, v[30:31], off
	v_add_u32_e32 v30, s1, v11
	v_ashrrev_i32_e32 v31, 31, v30
	v_lshlrev_b64 v[30:31], 13, v[30:31]
	v_lshl_add_u64 v[30:31], v[4:5], 0, v[30:31]
	v_add_u32_e32 v11, s57, v11


; __device__ void convert_wt(unsigned char* shm, const float* W, int K, int ldw, int c0, int ncols, bf16_t* Bt, int blk, int off) {
;     ...
;     for (int i = 0; i < 8; ++i) { const int e = tid + i * 512, r = e >> 6, c = e & 63; tile[r * 65 + c] = W[(size_t)(kt * 64 + r) * ldw + c0 + nt_ * 64 + c]; }
	global_load_dword v234, v[30:31], off
	v_add_u32_e32 v30, s1, v12
	v_ashrrev_i32_e32 v31, 31, v30
	v_lshlrev_b64 v[30:31], 13, v[30:31]
	v_lshl_add_u64 v[30:31], v[4:5], 0, v[30:31]
	v_add_u32_e32 v12, s57, v12


; __device__ void convert_wt(unsigned char* shm, const float* W, int K, int ldw, int c0, int ncols, bf16_t* Bt, int blk, int off) {
;     ...
;     for (int i = 0; i < 8; ++i) { const int e = tid + i * 512, r = e >> 6, c = e & 63; tile[r * 65 + c] = W[(size_t)(kt * 64 + r) * ldw + c0 + nt_ * 64 + c]; }
	global_load_dword v235, v[30:31], off
	v_add_u32_e32 v30, s1, v13
	v_ashrrev_i32_e32 v31, 31, v30
	v_lshlrev_b64 v[30:31], 13, v[30:31]
	v_lshl_add_u64 v[30:31], v[4:5], 0, v[30:31]
	v_add_u32_e32 v13, s57, v13


; __device__ void convert_wt(unsigned char* shm, const float* W, int K, int ldw, int c0, int ncols, bf16_t* Bt, int blk, int off) {
;     ...
;     for (int i = 0; i < 8; ++i) { const int e = tid + i * 512, r = e >> 6, c = e & 63; tile[r * 65 + c] = W[(size_t)(kt * 64 + r) * ldw + c0 + nt_ * 64 + c]; }
	global_load_dword v236, v[30:31], off
	v_add_u32_e32 v30, s1, v14
	v_ashrrev_i32_e32 v31, 31, v30
	v_lshlrev_b64 v[30:31], 13, v[30:31]
	v_lshl_add_u64 v[4:5], v[4:5], 0, v[30:31]
	v_add_u32_e32 v14, s57, v14


; __device__ void convert_wt(unsigned char* shm, const float* W, int K, int ldw, int c0, int ncols, bf16_t* Bt, int blk, int off) {
;     ...
;     for (int i = 0; i < 8; ++i) { const int e = tid + i * 512, r = e >> 6, c = e & 63; tile[r * 65 + c] = W[(size_t)(kt * 64 + r) * ldw + c0 + nt_ * 64 + c]; }
	global_load_dword v237, v[4:5], off
	s_waitcnt vmcnt(0)
	ds_write_b32 v22, v230
	ds_write_b32 v23, v231
	ds_write_b32 v24, v232
	ds_write_b32 v25, v233
	ds_write_b32 v26, v234
	ds_write_b32 v27, v235
	ds_write_b32 v28, v236
	ds_write_b32 v29, v237


; __device__ __forceinline__ unsigned cvt_pk_bf16(float lo, float hi) { unsigned r; asm volatile("v_cvt_pk_bf16_f32 %0, %1, %2" : "=v"(r) : "v"(lo), "v"(hi)); return r; }
; __device__ void convert_wt(unsigned char* shm, const float* W, int K, int ldw, int c0, int ncols, bf16_t* Bt, int blk, int off) {
;     ...
;     __syncthreads();
; #pragma unroll
;     for (int i = 0; i < 4; ++i) { const int e = tid + i * 512, n = e >> 5, kp = (e & 31) * 2; const int c = nt_ * 64 + n;
;       const unsigned w = cvt_pk_bf16(tile[kp * 65 + n], tile[(kp + 1) * 65 + n]);
;       const int nr = (c >> 7) * blk + off + (c & 127);
;       *(unsigned*)(Bt + ((size_t)((nr >> 8) * tk + kt) * 256 + (nr & 255)) * 64 + kp) = w; }
	s_waitcnt lgkmcnt(0)
	s_barrier
	v_add_u32_e32 v3, s0, v6
	ds_read2_b32 v[4:5], v15 offset1:65
	s_waitcnt lgkmcnt(0)
	v_cvt_pk_bf16_f32 v30, v4, v5
	v_ashrrev_i32_e32 v4, 5, v3
	v_and_b32_e32 v4, -8, v4
	v_subrev_u32_e32 v4, s7, v4
	v_add_u32_e32 v4, s5, v4
	v_ashrrev_i32_e32 v5, 31, v4
	v_lshlrev_b64 v[4:5], 15, v[4:5]
	v_lshlrev_b32_e32 v3, 7, v3
	v_lshl_add_u64 v[4:5], s[20:21], 0, v[4:5]
	v_and_b32_e32 v32, 0x7f80, v3
	v_lshl_add_u64 v[4:5], v[4:5], 0, v[32:33]
	v_mov_b32_e32 v3, v33
	v_lshl_add_u64 v[4:5], v[4:5], 0, v[2:3]
	global_store_dword v[4:5], v30, off
	v_add_u32_e32 v30, s0, v16
	ds_read2_b32 v[4:5], v17 offset1:65
	s_waitcnt lgkmcnt(0)
	v_cvt_pk_bf16_f32 v31, v4, v5
	v_ashrrev_i32_e32 v4, 5, v30
	v_and_b32_e32 v4, -8, v4
	v_subrev_u32_e32 v4, s7, v4
	v_add_u32_e32 v4, s5, v4
	v_ashrrev_i32_e32 v5, 31, v4
	v_lshlrev_b64 v[4:5], 15, v[4:5]
	v_lshlrev_b32_e32 v30, 7, v30
	v_lshl_add_u64 v[4:5], s[20:21], 0, v[4:5]
	v_and_b32_e32 v32, 0x7f80, v30
	v_lshl_add_u64 v[4:5], v[4:5], 0, v[32:33]
	v_lshl_add_u64 v[4:5], v[4:5], 0, v[2:3]
	global_store_dword v[4:5], v31, off
	v_add_u32_e32 v30, s0, v18
	ds_read2_b32 v[4:5], v19 offset1:65
	s_waitcnt lgkmcnt(0)
	v_cvt_pk_bf16_f32 v31, v4, v5
	v_ashrrev_i32_e32 v4, 5, v30
	v_and_b32_e32 v4, -8, v4
	v_subrev_u32_e32 v4, s7, v4
	v_add_u32_e32 v4, s5, v4
	v_ashrrev_i32_e32 v5, 31, v4
	v_lshlrev_b64 v[4:5], 15, v[4:5]
	v_lshlrev_b32_e32 v30, 7, v30
	v_lshl_add_u64 v[4:5], s[20:21], 0, v[4:5]
	v_and_b32_e32 v32, 0x7f80, v30
	v_lshl_add_u64 v[4:5], v[4:5], 0, v[32:33]
	v_lshl_add_u64 v[4:5], v[4:5], 0, v[2:3]
	global_store_dword v[4:5], v31, off
	v_add_u32_e32 v30, s0, v20
	ds_read2_b32 v[4:5], v21 offset1:65
	s_waitcnt lgkmcnt(0)
	v_cvt_pk_bf16_f32 v31, v4, v5
	v_ashrrev_i32_e32 v4, 5, v30
	v_and_b32_e32 v4, -8, v4
	v_subrev_u32_e32 v4, s7, v4
	v_add_u32_e32 v4, s5, v4
	v_ashrrev_i32_e32 v5, 31, v4
	v_lshlrev_b64 v[4:5], 15, v[4:5]
	v_lshlrev_b32_e32 v30, 7, v30
	v_lshl_add_u64 v[4:5], s[20:21], 0, v[4:5]
	v_and_b32_e32 v32, 0x7f80, v30
	v_lshl_add_u64 v[4:5], v[4:5], 0, v[32:33]
	s_add_i32 s5, s5, s14
	v_lshl_add_u64 v[4:5], v[4:5], 0, v[2:3]
	s_cmpk_lt_i32 s5, 0x100
	global_store_dword v[4:5], v31, off
	s_cbranch_scc1 .LBB0_1266
	s_movk_i32 s64, 0x5800

; __device__ void convert_wt(unsigned char* shm, const float* W, int K, int ldw, int c0, int ncols, bf16_t* Bt, int blk, int off) {
;     ...
;   for (int t = blockIdx.x; t < ntile; t += gridDim.x) {
;     const int kt = t % tk, nt_ = t / tk;
;     __syncthreads();
; #pragma unroll
;     for (int i = 0; i < 8; ++i) { const int e = tid + i * 512, r = e >> 6, c = e & 63; tile[r * 65 + c] = W[(size_t)(kt * 64 + r) * ldw + c0 + nt_ * 64 + c]; }
.LBB0_1270:
	s_ashr_i32 s0, s5, 31
	s_lshr_b32 s0, s0, 27
	s_add_i32 s7, s5, s0
	s_ashr_i32 s11, s7, 5
	s_lshl_b32 s0, s11, 6
	s_ashr_i32 s1, s0, 31
	v_lshl_add_u64 v[4:5], s[0:1], 2, v[0:1]
	s_lshl_b32 s1, s11, 11
	s_sub_i32 s1, s17, s1
	v_add_u32_e32 v30, s1, v7
	v_ashrrev_i32_e32 v31, 31, v30
	v_lshlrev_b64 v[30:31], 13, v[30:31]
	v_lshl_add_u64 v[30:31], v[4:5], 0, v[30:31]
	s_barrier
	global_load_dword v230, v[30:31], off
	v_add_u32_e32 v30, s1, v8
	v_ashrrev_i32_e32 v31, 31, v30
	v_lshlrev_b64 v[30:31], 13, v[30:31]
	v_lshl_add_u64 v[30:31], v[4:5], 0, v[30:31]
	s_andn2_b32 s7, s7, 31
	v_add_u32_e32 v8, s57, v8
	v_add_u32_e32 v7, s57, v7


; __device__ void convert_wt(unsigned char* shm, const float* W, int K, int ldw, int c0, int ncols, bf16_t* Bt, int blk, int off) {
;     ...
;     for (int i = 0; i < 8; ++i) { const int e = tid + i * 512, r = e >> 6, c = e & 63; tile[r * 65 + c] = W[(size_t)(kt * 64 + r) * ldw + c0 + nt_ * 64 + c]; }
	global_load_dword v231, v[30:31], off
	v_add_u32_e32 v30, s1, v9
	v_ashrrev_i32_e32 v31, 31, v30
	v_lshlrev_b64 v[30:31], 13, v[30:31]
	v_lshl_add_u64 v[30:31], v[4:5], 0, v[30:31]
	v_add_u32_e32 v9, s57, v9


; __device__ void convert_wt(unsigned char* shm, const float* W, int K, int ldw, int c0, int ncols, bf16_t* Bt, int blk, int off) {
;     ...
;     for (int i = 0; i < 8; ++i) { const int e = tid + i * 512, r = e >> 6, c = e & 63; tile[r * 65 + c] = W[(size_t)(kt * 64 + r) * ldw + c0 + nt_ * 64 + c]; }
	global_load_dword v232, v[30:31], off
	v_add_u32_e32 v30, s1, v10
	v_ashrrev_i32_e32 v31, 31, v30
	v_lshlrev_b64 v[30:31], 13, v[30:31]
	v_lshl_add_u64 v[30:31], v[4:5], 0, v[30:31]
	v_add_u32_e32 v10, s57, v10


; __device__ void convert_wt(unsigned char* shm, const float* W, int K, int ldw, int c0, int ncols, bf16_t* Bt, int blk, int off) {
;     ...
;     for (int i = 0; i < 8; ++i) { const int e = tid + i * 512, r = e >> 6, c = e & 63; tile[r * 65 + c] = W[(size_t)(kt * 64 + r) * ldw + c0 + nt_ * 64 + c]; }
	global_load_dword v233, v[30:31], off
	v_add_u32_e32 v30, s1, v11
	v_ashrrev_i32_e32 v31, 31, v30
	v_lshlrev_b64 v[30:31], 13, v[30:31]
	v_lshl_add_u64 v[30:31], v[4:5], 0, v[30:31]
	v_add_u32_e32 v11, s57, v11


; __device__ void convert_wt(unsigned char* shm, const float* W, int K, int ldw, int c0, int ncols, bf16_t* Bt, int blk, int off) {
;     ...
;     for (int i = 0; i < 8; ++i) { const int e = tid + i * 512, r = e >> 6, c = e & 63; tile[r * 65 + c] = W[(size_t)(kt * 64 + r) * ldw + c0 + nt_ * 64 + c]; }
	global_load_dword v234, v[30:31], off
	v_add_u32_e32 v30, s1, v12
	v_ashrrev_i32_e32 v31, 31, v30
	v_lshlrev_b64 v[30:31], 13, v[30:31]
	v_lshl_add_u64 v[30:31], v[4:5], 0, v[30:31]
	v_add_u32_e32 v12, s57, v12


; __device__ void convert_wt(unsigned char* shm, const float* W, int K, int ldw, int c0, int ncols, bf16_t* Bt, int blk, int off) {
;     ...
;     for (int i = 0; i < 8; ++i) { const int e = tid + i * 512, r = e >> 6, c = e & 63; tile[r * 65 + c] = W[(size_t)(kt * 64 + r) * ldw + c0 + nt_ * 64 + c]; }
	global_load_dword v235, v[30:31], off
	v_add_u32_e32 v30, s1, v13
	v_ashrrev_i32_e32 v31, 31, v30
	v_lshlrev_b64 v[30:31], 13, v[30:31]
	v_lshl_add_u64 v[30:31], v[4:5], 0, v[30:31]
	v_add_u32_e32 v13, s57, v13


; __device__ void convert_wt(unsigned char* shm, const float* W, int K, int ldw, int c0, int ncols, bf16_t* Bt, int blk, int off) {
;     ...
;     for (int i = 0; i < 8; ++i) { const int e = tid + i * 512, r = e >> 6, c = e & 63; tile[r * 65 + c] = W[(size_t)(kt * 64 + r) * ldw + c0 + nt_ * 64 + c]; }
	global_load_dword v236, v[30:31], off
	v_add_u32_e32 v30, s1, v14
	v_ashrrev_i32_e32 v31, 31, v30
	v_lshlrev_b64 v[30:31], 13, v[30:31]
	v_lshl_add_u64 v[4:5], v[4:5], 0, v[30:31]
	v_add_u32_e32 v14, s57, v14


; __device__ void convert_wt(unsigned char* shm, const float* W, int K, int ldw, int c0, int ncols, bf16_t* Bt, int blk, int off) {
;     ...
;     for (int i = 0; i < 8; ++i) { const int e = tid + i * 512, r = e >> 6, c = e & 63; tile[r * 65 + c] = W[(size_t)(kt * 64 + r) * ldw + c0 + nt_ * 64 + c]; }
	global_load_dword v237, v[4:5], off
	s_waitcnt vmcnt(0)
	ds_write_b32 v22, v230
	ds_write_b32 v23, v231
	ds_write_b32 v24, v232
	ds_write_b32 v25, v233
	ds_write_b32 v26, v234
	ds_write_b32 v27, v235
	ds_write_b32 v28, v236
	ds_write_b32 v29, v237


; __device__ __forceinline__ unsigned cvt_pk_bf16(float lo, float hi) { unsigned r; asm volatile("v_cvt_pk_bf16_f32 %0, %1, %2" : "=v"(r) : "v"(lo), "v"(hi)); return r; }
; __device__ void convert_wt(unsigned char* shm, const float* W, int K, int ldw, int c0, int ncols, bf16_t* Bt, int blk, int off) {
;     ...
;     __syncthreads();
; #pragma unroll
;     for (int i = 0; i < 4; ++i) { const int e = tid + i * 512, n = e >> 5, kp = (e & 31) * 2; const int c = nt_ * 64 + n;
;       const unsigned w = cvt_pk_bf16(tile[kp * 65 + n], tile[(kp + 1) * 65 + n]);
;       const int nr = (c >> 7) * blk + off + (c & 127);
;       *(unsigned*)(Bt + ((size_t)((nr >> 8) * tk + kt) * 256 + (nr & 255)) * 64 + kp) = w; }
	s_waitcnt lgkmcnt(0)
	s_barrier
	v_add_u32_e32 v3, s0, v6
	ds_read2_b32 v[4:5], v15 offset1:65
	s_waitcnt lgkmcnt(0)
	v_cvt_pk_bf16_f32 v30, v4, v5
	v_ashrrev_i32_e32 v4, 3, v3
	v_and_b32_e32 v4, 0xffffffe0, v4
	v_subrev_u32_e32 v4, s7, v4
	v_add_u32_e32 v4, s5, v4
	v_ashrrev_i32_e32 v5, 31, v4
	v_lshlrev_b64 v[4:5], 15, v[4:5]
	v_lshlrev_b32_e32 v3, 7, v3
	v_lshl_add_u64 v[4:5], s[20:21], 0, v[4:5]
	v_and_b32_e32 v32, 0x7f80, v3
	v_lshl_add_u64 v[4:5], v[4:5], 0, v[32:33]
	v_mov_b32_e32 v3, v33
	v_lshl_add_u64 v[4:5], v[4:5], 0, v[2:3]
	global_store_dword v[4:5], v30, off
	v_add_u32_e32 v30, s0, v16
	ds_read2_b32 v[4:5], v17 offset1:65
	s_waitcnt lgkmcnt(0)
	v_cvt_pk_bf16_f32 v31, v4, v5
	v_ashrrev_i32_e32 v4, 3, v30
	v_and_b32_e32 v4, 0xffffffe0, v4
	v_subrev_u32_e32 v4, s7, v4
	v_add_u32_e32 v4, s5, v4
	v_ashrrev_i32_e32 v5, 31, v4
	v_lshlrev_b64 v[4:5], 15, v[4:5]
	v_lshlrev_b32_e32 v30, 7, v30
	v_lshl_add_u64 v[4:5], s[20:21], 0, v[4:5]
	v_and_b32_e32 v32, 0x7f80, v30
	v_lshl_add_u64 v[4:5], v[4:5], 0, v[32:33]
	v_lshl_add_u64 v[4:5], v[4:5], 0, v[2:3]
	global_store_dword v[4:5], v31, off
	v_add_u32_e32 v30, s0, v18
	ds_read2_b32 v[4:5], v19 offset1:65
	s_waitcnt lgkmcnt(0)
	v_cvt_pk_bf16_f32 v31, v4, v5
	v_ashrrev_i32_e32 v4, 3, v30
	v_and_b32_e32 v4, 0xffffffe0, v4
	v_subrev_u32_e32 v4, s7, v4
	v_add_u32_e32 v4, s5, v4
	v_ashrrev_i32_e32 v5, 31, v4
	v_lshlrev_b64 v[4:5], 15, v[4:5]
	v_lshlrev_b32_e32 v30, 7, v30
	v_lshl_add_u64 v[4:5], s[20:21], 0, v[4:5]
	v_and_b32_e32 v32, 0x7f80, v30
	v_lshl_add_u64 v[4:5], v[4:5], 0, v[32:33]
	v_lshl_add_u64 v[4:5], v[4:5], 0, v[2:3]
	global_store_dword v[4:5], v31, off
	v_add_u32_e32 v30, s0, v20
	ds_read2_b32 v[4:5], v21 offset1:65
	s_waitcnt lgkmcnt(0)
	v_cvt_pk_bf16_f32 v31, v4, v5
	v_ashrrev_i32_e32 v4, 3, v30
	v_and_b32_e32 v4, 0xffffffe0, v4
	v_subrev_u32_e32 v4, s7, v4
	v_add_u32_e32 v4, s5, v4
	v_ashrrev_i32_e32 v5, 31, v4
	v_lshlrev_b64 v[4:5], 15, v[4:5]
	v_lshlrev_b32_e32 v30, 7, v30
	v_lshl_add_u64 v[4:5], s[20:21], 0, v[4:5]
	v_and_b32_e32 v32, 0x7f80, v30
	v_lshl_add_u64 v[4:5], v[4:5], 0, v[32:33]
	s_add_i32 s5, s5, s14
	v_lshl_add_u64 v[4:5], v[4:5], 0, v[2:3]
	s_cmpk_lt_i32 s5, 0x400
	global_store_dword v[4:5], v31, off
	s_cbranch_scc1 .LBB0_1270
